# stagger in the diff-attention stage loop: waves 0-3 run QK, softmax, P.V in-stage; waves 4-7 run QK, deferred P.V of the previous stage, then softmax, so SIMD partners alternate matrix and vector work
# speedup vs baseline: 1.0162x; 1.0162x over previous
; #define DF_WAITBAR(N) asm volatile("s_waitcnt vmcnt(" #N ") lgkmcnt(0)\n\ts_barrier" ::: "memory")
; DI void diff_unit(const Args& A, const bf16_t* QKV, bf16_t* ATT, unsigned char* lds, LAS unsigned char* lds3, int b, int head, int qb, int tid, int wid, int lane) {
;     const int r32 = lane & 31, hi = lane >> 5, comp = wid >> 2, wq = wid & 3;
;     const size_t rowbase = (size_t)b * SEQ;
;     const int q0 = qb * 128 + wq * 32;
;     const int qcol = 1536 + head * 128 + comp * 64;
;     bf16x8 qf[4];
; #pragma unroll
;     for (int c = 0; c < 4; ++c) qf[c] = *(const bf16x8*)(QKV + (rowbase + q0 + r32) * QKVW + qcol + 16 * c + 8 * hi);
;     f32x16 o[4];
; #pragma unroll
;     for (int t = 0; t < 4; ++t)
; #pragma unroll
;         for (int i = 0; i < 16; ++i) o[t][i] = 0.f;
;     float m = -INFINITY, l = 0.f;
;     const int nst = 2 * (qb + 1);
;     const unsigned ldsb = (unsigned)(uintptr_t)lds3;
;     const int kkey = 8 * wid + (lane >> 3), kch = (lane & 7) ^ ((kkey >> 1) & 7);
;     const int vi0 = 2 * wid, vi1 = 2 * wid + 1;
;     const bf16_t* sbase = QKV + rowbase * QKVW + head * 128;
;     const unsigned oK = (unsigned)((kkey * QKVW + 2048 + kch * 8) * 2);
;     const unsigned oV0 = (unsigned)(((16 * (vi0 & 3) + (lane >> 2)) * QKVW + 2560 + ((vi0 >> 2) * 4 + (lane & 3)) * 8) * 2);
;     const unsigned oV1 = (unsigned)(((16 * (vi1 & 3) + (lane >> 2)) * QKVW + 2560 + ((vi1 >> 2) * 4 + (lane & 3)) * 8) * 2);
;     const unsigned dK = (unsigned)__builtin_amdgcn_readfirstlane(wid * 1024);
;     const unsigned dV0 = (unsigned)__builtin_amdgcn_readfirstlane(DF_V + (vi0 >> 2) * 4096 + (vi0 & 3) * 1024), dV1 = (unsigned)__builtin_amdgcn_readfirstlane(DF_V + (vi1 >> 2) * 4096 + (vi1 & 3) * 1024);
;     ...
;     DF_DMA(0, 0); DF_DMA(1, 1);
;     asm volatile("" : "+v"(qf[0]), "+v"(qf[1]), "+v"(qf[2]), "+v"(qf[3]));
;     DF_WAITBAR(4);
;     const int vlane = (4 * hi + ((lane & 15) >> 2)) * 64 + ((lane >> 4) & 1) * 32 + (lane & 3) * 8;
;     const bool skew = false;
;     bf16x8 pp[4]; { const bf16x8 z8 = {0, 0, 0, 0, 0, 0, 0, 0}; pp[0] = z8; pp[1] = z8; pp[2] = z8; pp[3] = z8; } int pvo = vlane; bool have_prev = false;
;     for (int t = 0; t < nst; ++t) {
;         { const int tl = (t + 2 < nst) ? t + 2 : nst - 1; DF_DMA(tl, (t + 2) & 3); }
.LBB0_278:
	s_and_b32 s49, s7, 63
	s_ashr_i32 s6, s7, 8
	s_xor_b32 s24, s49, 0x7f
	s_bfe_u32 s22, s7, 0x20006
	s_ashr_i32 s7, s6, 31
	s_lshl_b32 s25, s24, 7
	s_lshl_b64 s[26:27], s[6:7], 14
	s_or_b32 s7, s25, s34
	v_or_b32_e32 v1, s7, v129
	s_lshl_b32 s48, s22, 7
	v_or_b32_e32 v154, s26, v1
	v_mad_u64_u32 v[2:3], s[8:9], v154, s43, v[140:141]
	s_add_u32 s28, s35, s48
	v_mad_i32_i24 v3, s27, v169, v3
	s_addc_u32 s29, s42, 0
	v_lshl_add_u64 v[2:3], s[28:29], 1, v[2:3]
	v_lshl_add_u64 v[2:3], v[2:3], 0, v[144:145]
	global_load_dwordx4 v[112:115], v[2:3], off offset:3168
	global_load_dwordx4 v[116:119], v[2:3], off offset:3136
	global_load_dwordx4 v[120:123], v[2:3], off offset:3104
	global_load_dwordx4 v[124:127], v[2:3], off offset:3072
	s_mul_hi_i32 s31, s6, 0x6000000
	s_mul_i32 s50, s6, 0x6000000
	s_lshl_b32 s6, s24, 1
	s_add_u32 s24, s12, s50
	v_add_u32_e32 v146, s25, v168
	s_addc_u32 s25, s13, s31
	s_lshl_b32 s22, s22, 8
	v_readfirstlane_b32 s30, v170
	s_add_u32 s24, s24, s22
	s_addc_u32 s25, s25, 0
	s_lshl_b32 s50, s30, 10
	s_mov_b32 s30, m0
	s_mov_b32 m0, s50
	s_nop 0
	global_load_lds_dwordx4 v156, s[24:25]
	s_mov_b32 m0, s30
	s_add_i32 s51, s50, 0x2000
	s_mov_b32 s30, m0
	s_mov_b32 m0, s51
	s_nop 0
	global_load_lds_dwordx4 v159, s[24:25]
	s_mov_b32 m0, s30
	v_readfirstlane_b32 s9, v171
	s_mov_b32 s31, m0
	s_mov_b32 m0, s9
	s_nop 0
	global_load_lds_dwordx4 v157, s[24:25]
	s_mov_b32 m0, s31
	v_readfirstlane_b32 s10, v172
	s_add_u32 s30, s24, 0x60000
	s_mov_b32 s58, m0
	s_mov_b32 m0, s10
	s_nop 0
	global_load_lds_dwordx4 v158, s[24:25]
	s_mov_b32 m0, s58
	s_addc_u32 s31, s25, 0
	s_add_i32 s54, s50, 0x8000
	s_mov_b32 s58, m0
	s_mov_b32 m0, s54
	s_nop 0
	global_load_lds_dwordx4 v156, s[30:31]
	s_mov_b32 m0, s58
	s_add_i32 s55, s50, 0xa000
	s_mov_b32 s54, m0
	s_mov_b32 m0, s55
	s_nop 0
	global_load_lds_dwordx4 v159, s[30:31]
	s_mov_b32 m0, s54
	s_add_i32 s56, s9, 0x8000
	s_mov_b32 s54, m0
	s_mov_b32 m0, s56
	s_nop 0
	global_load_lds_dwordx4 v157, s[30:31]
	s_mov_b32 m0, s54
	v_mov_b32_e32 v14, v0
	v_mov_b32_e32 v15, v0
	s_add_i32 s57, s10, 0x8000
	s_mov_b32 s54, m0
	s_mov_b32 m0, s57
	s_nop 0
	global_load_lds_dwordx4 v158, s[30:31]
	s_mov_b32 m0, s54
	v_mov_b32_e32 v1, v0
	v_mov_b32_e32 v2, v0
	v_mov_b32_e32 v3, v0
	v_mov_b32_e32 v4, v0
	v_mov_b32_e32 v5, v0
	v_mov_b32_e32 v6, v0
	v_mov_b32_e32 v7, v0
	v_mov_b32_e32 v8, v0
	v_mov_b32_e32 v9, v0
	v_mov_b32_e32 v10, v0
	v_mov_b32_e32 v11, v0
	v_mov_b32_e32 v12, v0
	v_mov_b32_e32 v13, v0
	v_mov_b64_e32 v[30:31], v[14:15]
	v_mov_b64_e32 v[46:47], v[14:15]
	v_mov_b64_e32 v[62:63], v[14:15]
	v_mov_b64_e32 v[78:79], v[14:15]
	s_mov_b32 s8, 63
	s_mov_b32 s11, 0
	v_mov_b32_e32 v143, 0
	v_mov_b32_e32 v147, 0xff800000
	v_mov_b64_e32 v[28:29], v[12:13]
	v_mov_b64_e32 v[26:27], v[10:11]
	v_mov_b64_e32 v[24:25], v[8:9]
	v_mov_b64_e32 v[22:23], v[6:7]
	v_mov_b64_e32 v[20:21], v[4:5]
	v_mov_b64_e32 v[18:19], v[2:3]
	v_mov_b64_e32 v[16:17], v[0:1]
	v_mov_b32_e32 v155, s27
	s_or_b32 s52, s6, 1
	s_or_b32 s53, s7, 31
	v_mov_b64_e32 v[44:45], v[12:13]
	v_mov_b64_e32 v[42:43], v[10:11]
	v_mov_b64_e32 v[40:41], v[8:9]
	v_mov_b64_e32 v[38:39], v[6:7]
	v_mov_b64_e32 v[36:37], v[4:5]
	v_mov_b64_e32 v[34:35], v[2:3]
	v_mov_b64_e32 v[32:33], v[0:1]
	v_mov_b64_e32 v[60:61], v[12:13]
	v_mov_b64_e32 v[58:59], v[10:11]
	v_mov_b64_e32 v[56:57], v[8:9]
	s_waitcnt vmcnt(0)
	s_waitcnt vmcnt(4) lgkmcnt(0)
	s_barrier
	v_mov_b64_e32 v[54:55], v[6:7]
	v_mov_b64_e32 v[52:53], v[4:5]
	v_mov_b64_e32 v[50:51], v[2:3]
	v_mov_b64_e32 v[48:49], v[0:1]
	s_mov_b32 s54, 0
	v_mov_b64_e32 v[76:77], v[12:13]
	v_mov_b64_e32 v[74:75], v[10:11]
	v_mov_b64_e32 v[72:73], v[8:9]
	v_mov_b64_e32 v[70:71], v[6:7]
	v_mov_b64_e32 v[68:69], v[4:5]
	v_mov_b64_e32 v[66:67], v[2:3]
	v_mov_b64_e32 v[64:65], v[0:1]
	s_mov_b32 s60, 0
	s_mov_b32 s61, 0
	s_mov_b32 s62, m0
	v_mov_b32_e32 v240, 0
	v_mov_b32_e32 v241, 0
	v_mov_b32_e32 v242, 0
	v_mov_b32_e32 v243, 0
	v_mov_b32_e32 v244, 0
	v_mov_b32_e32 v245, 0
	v_mov_b32_e32 v246, 0
	v_mov_b32_e32 v247, 0
	v_mov_b32_e32 v248, 0
	v_mov_b32_e32 v249, 0
	v_mov_b32_e32 v250, 0
	v_mov_b32_e32 v251, 0
	v_mov_b32_e32 v252, 0
	v_mov_b32_e32 v253, 0
	v_mov_b32_e32 v254, 0
	v_mov_b32_e32 v255, 0
	s_add_i32 s66, s54, 2
	s_cmp_lt_u32 s54, s6
	s_cselect_b32 s64, s66, s52
	s_lshl_b32 s65, s64, 6
	s_mul_i32 s64, s64, 0x60000
	s_mul_hi_u32 s65, s65, 0x1800
	s_add_u32 s64, s24, s64
	s_addc_u32 s65, s25, s65
	s_lshl_b32 s66, s66, 15
	s_and_b32 s66, s66, 0x18000
	s_add_i32 s67, s66, s50
	s_add_i32 s68, s66, s51
	s_add_i32 s69, s66, s9
	s_add_i32 s70, s66, s10
	s_and_b64 vcc, exec, s[20:21]
	s_cbranch_vccnz .Ldf1a_loop

; DI f32x16 mfma32(bf16x8 a, bf16x8 b, f32x16 c) { return __builtin_amdgcn_mfma_f32_32x32x16_bf16(a, b, c, 0, 0, 0); }
; #define DF_VLD(VF, VOFF, H) do { _Pragma("unroll") for (int d2 = 0; d2 < 2; ++d2) { LAS unsigned char* vb_ = lds3 + (VOFF) + (2 * (H) + d2) * 4096; VF[2 * d2] = vfrag(vb_); VF[2 * d2 + 1] = vfrag(vb_ + 1024); } } while (0)
; #define DF_PVM(VF, P0, P1, H) do { _Pragma("unroll") for (int d2 = 0; d2 < 2; ++d2) { o[2 * (H) + d2] = mfma32(VF[2 * d2], P0, o[2 * (H) + d2]); o[2 * (H) + d2] = mfma32(VF[2 * d2 + 1], P1, o[2 * (H) + d2]); } } while (0)
; DI void diff_stage(const unsigned char* lds, LAS unsigned char* lds3, int buf, int t, int comp, int q0, int r32, int hi, int vlane, bool skew,
;                    const bf16x8 (&qf)[4], f32x16 (&o)[4], float& m, float& l, bf16x8 (&pp)[4], int& pvo, bool& have_prev) {
;     ...
;     if (skew && have_prev) {
; #pragma unroll
;         for (int sub = 0; sub < 2; ++sub) { DF_VLD(vf, pvo + sub * 2048, 0); DF_PVM(vf, pp[2 * sub], pp[2 * sub + 1], 0); DF_VLD(vf, pvo + sub * 2048, 1); DF_PVM(vf, pp[2 * sub], pp[2 * sub + 1], 1); }
;     }
;     f32x16 s0, s1;
; #pragma unroll
;     for (int i = 0; i < 16; ++i) { s0[i] = 0.f; s1[i] = 0.f; }
;     {
;         bf16x8 k0f[4], k1f[4];
; #pragma unroll
;         for (int c = 0; c < 4; ++c) { k0f[c] = *(const bf16x8*)(sb + ((32 * c) ^ ke16)); k1f[c] = *(const bf16x8*)(sb + 32 * 128 + ((32 * c) ^ ke16)); }
; #pragma unroll
;         for (int c = 0; c < 4; ++c) { s0 = mfma32(k0f[c], qf[c], s0); s1 = mfma32(k1f[c], qf[c], s1); }
;     }
;     if (k0 + 63 > q0) {
;         const int dq = q0 + r32 - k0 - 4 * hi;
; #pragma unroll
;         for (int i = 0; i < 16; ++i) { const int ci = (i & 3) + 8 * (i >> 2); s0[i] = (ci > dq) ? -INFINITY : s0[i]; s1[i] = (ci + 32 > dq) ? -INFINITY : s1[i]; }
.Ldf1bs_noresc:
	s_waitcnt lgkmcnt(7)
	v_mfma_f32_32x32x16_bf16 v[96:111], v[208:211], v[124:127], 0
	s_waitcnt lgkmcnt(6)
	v_mfma_f32_32x32x16_bf16 v[80:95], v[212:215], v[124:127], 0
	s_waitcnt lgkmcnt(5)
	v_mfma_f32_32x32x16_bf16 v[96:111], v[216:219], v[120:123], v[96:111]
	s_waitcnt lgkmcnt(4)
	v_mfma_f32_32x32x16_bf16 v[80:95], v[220:223], v[120:123], v[80:95]
	s_waitcnt lgkmcnt(3)
	v_mfma_f32_32x32x16_bf16 v[96:111], v[224:227], v[116:119], v[96:111]
	s_waitcnt lgkmcnt(2)
	v_mfma_f32_32x32x16_bf16 v[80:95], v[228:231], v[116:119], v[80:95]
	s_waitcnt lgkmcnt(1)
	v_mfma_f32_32x32x16_bf16 v[96:111], v[232:235], v[112:115], v[96:111]
	s_waitcnt lgkmcnt(0)
	v_mfma_f32_32x32x16_bf16 v[80:95], v[236:239], v[112:115], v[80:95]
	ds_read_b64_tr_b16 v[208:209], v6 offset:16384
	ds_read_b64_tr_b16 v[210:211], v6 offset:16896
	ds_read_b64_tr_b16 v[212:213], v6 offset:17408
	ds_read_b64_tr_b16 v[214:215], v6 offset:17920
	ds_read_b64_tr_b16 v[216:217], v6 offset:20480
	ds_read_b64_tr_b16 v[218:219], v6 offset:20992
	ds_read_b64_tr_b16 v[220:221], v6 offset:21504
	ds_read_b64_tr_b16 v[222:223], v6 offset:22016
	ds_read_b64_tr_b16 v[224:225], v6 offset:24576
	ds_read_b64_tr_b16 v[226:227], v6 offset:25088
	ds_read_b64_tr_b16 v[228:229], v6 offset:25600
	ds_read_b64_tr_b16 v[230:231], v6 offset:26112
	s_waitcnt lgkmcnt(10)
	v_mfma_f32_32x32x16_bf16 v[64:79], v[208:211], v[240:243], v[64:79]
	ds_read_b64_tr_b16 v[232:233], v6 offset:28672
	ds_read_b64_tr_b16 v[234:235], v6 offset:29184
	s_waitcnt lgkmcnt(10)
	v_mfma_f32_32x32x16_bf16 v[64:79], v[212:215], v[244:247], v[64:79]
	ds_read_b64_tr_b16 v[236:237], v6 offset:29696
	ds_read_b64_tr_b16 v[238:239], v6 offset:30208
	s_waitcnt lgkmcnt(10)
	v_mfma_f32_32x32x16_bf16 v[48:63], v[216:219], v[240:243], v[48:63]
	ds_read_b64_tr_b16 v[208:209], v6 offset:18432
	ds_read_b64_tr_b16 v[210:211], v6 offset:18944
	s_waitcnt lgkmcnt(10)
	v_mfma_f32_32x32x16_bf16 v[48:63], v[220:223], v[244:247], v[48:63]
	ds_read_b64_tr_b16 v[212:213], v6 offset:19456
	ds_read_b64_tr_b16 v[214:215], v6 offset:19968
	s_waitcnt lgkmcnt(10)
	v_mfma_f32_32x32x16_bf16 v[32:47], v[224:227], v[240:243], v[32:47]
	ds_read_b64_tr_b16 v[216:217], v6 offset:22528
	ds_read_b64_tr_b16 v[218:219], v6 offset:23040
	s_waitcnt lgkmcnt(10)
	v_mfma_f32_32x32x16_bf16 v[32:47], v[228:231], v[244:247], v[32:47]
	ds_read_b64_tr_b16 v[220:221], v6 offset:23552
	ds_read_b64_tr_b16 v[222:223], v6 offset:24064
	s_waitcnt lgkmcnt(10)
	v_mfma_f32_32x32x16_bf16 v[16:31], v[232:235], v[240:243], v[16:31]
	ds_read_b64_tr_b16 v[224:225], v6 offset:26624
	ds_read_b64_tr_b16 v[226:227], v6 offset:27136
	s_waitcnt lgkmcnt(10)
	v_mfma_f32_32x32x16_bf16 v[16:31], v[236:239], v[244:247], v[16:31]
	ds_read_b64_tr_b16 v[228:229], v6 offset:27648
	ds_read_b64_tr_b16 v[230:231], v6 offset:28160
	s_waitcnt lgkmcnt(10)
	v_mfma_f32_32x32x16_bf16 v[64:79], v[208:211], v[248:251], v[64:79]
	ds_read_b64_tr_b16 v[232:233], v6 offset:30720
	ds_read_b64_tr_b16 v[234:235], v6 offset:31232
	s_waitcnt lgkmcnt(10)
	v_mfma_f32_32x32x16_bf16 v[64:79], v[212:215], v[252:255], v[64:79]
	ds_read_b64_tr_b16 v[236:237], v6 offset:31744
	ds_read_b64_tr_b16 v[238:239], v6 offset:32256
	s_waitcnt lgkmcnt(10)
	v_mfma_f32_32x32x16_bf16 v[48:63], v[216:219], v[248:251], v[48:63]
	s_waitcnt lgkmcnt(8)
	v_mfma_f32_32x32x16_bf16 v[48:63], v[220:223], v[252:255], v[48:63]
	s_waitcnt lgkmcnt(6)
	v_mfma_f32_32x32x16_bf16 v[32:47], v[224:227], v[248:251], v[32:47]
	s_waitcnt lgkmcnt(4)
	v_mfma_f32_32x32x16_bf16 v[32:47], v[228:231], v[252:255], v[32:47]
	s_waitcnt lgkmcnt(2)
	v_mfma_f32_32x32x16_bf16 v[16:31], v[232:235], v[248:251], v[16:31]
	s_waitcnt lgkmcnt(0)
	v_mfma_f32_32x32x16_bf16 v[16:31], v[236:239], v[252:255], v[16:31]
	s_cmp_le_u32 s8, s7
	s_cbranch_scc1 .Ldf1b_nodiag
	s_nop 7
	v_cmp_lt_i32_e32 vcc, -1, v146
	s_nop 1
	v_cndmask_b32_e32 v96, v176, v96, vcc
	v_cmp_lt_i32_e32 vcc, 31, v146
	s_nop 1
	v_cndmask_b32_e32 v80, v176, v80, vcc
	v_cmp_lt_i32_e32 vcc, 0, v146
	s_nop 1
	v_cndmask_b32_e32 v97, v176, v97, vcc
	v_cmp_lt_i32_e32 vcc, 32, v146
	s_nop 1
	v_cndmask_b32_e32 v81, v176, v81, vcc
	v_cmp_lt_i32_e32 vcc, 1, v146
	s_nop 1
	v_cndmask_b32_e32 v98, v176, v98, vcc
	v_cmp_lt_i32_e32 vcc, 33, v146
	s_nop 1
	v_cndmask_b32_e32 v82, v176, v82, vcc
	v_cmp_lt_i32_e32 vcc, 2, v146
	s_nop 1
	v_cndmask_b32_e32 v99, v176, v99, vcc
	v_cmp_lt_i32_e32 vcc, 34, v146
	s_nop 1
	v_cndmask_b32_e32 v83, v176, v83, vcc
	v_cmp_lt_i32_e32 vcc, 7, v146
	s_nop 1
	v_cndmask_b32_e32 v100, v176, v100, vcc
	v_cmp_lt_i32_e32 vcc, 39, v146
	s_nop 1
	v_cndmask_b32_e32 v84, v176, v84, vcc
	v_cmp_lt_i32_e32 vcc, 8, v146
	s_nop 1
	v_cndmask_b32_e32 v101, v176, v101, vcc
	v_cmp_lt_i32_e32 vcc, 40, v146
	s_nop 1
	v_cndmask_b32_e32 v85, v176, v85, vcc
	v_cmp_lt_i32_e32 vcc, 9, v146
	s_nop 1
	v_cndmask_b32_e32 v102, v176, v102, vcc
	v_cmp_lt_i32_e32 vcc, 41, v146
	s_nop 1
	v_cndmask_b32_e32 v86, v176, v86, vcc
	v_cmp_lt_i32_e32 vcc, 10, v146
	s_nop 1
	v_cndmask_b32_e32 v103, v176, v103, vcc
	v_cmp_lt_i32_e32 vcc, 42, v146
	s_nop 1
	v_cndmask_b32_e32 v87, v176, v87, vcc
	v_cmp_lt_i32_e32 vcc, 15, v146
	s_nop 1
	v_cndmask_b32_e32 v104, v176, v104, vcc
	v_cmp_lt_i32_e32 vcc, 47, v146
	s_nop 1
	v_cndmask_b32_e32 v88, v176, v88, vcc
	v_cmp_lt_i32_e32 vcc, 16, v146
	s_nop 1
	v_cndmask_b32_e32 v105, v176, v105, vcc
	v_cmp_lt_i32_e32 vcc, 48, v146
	s_nop 1
	v_cndmask_b32_e32 v89, v176, v89, vcc
	v_cmp_lt_i32_e32 vcc, 17, v146
	s_nop 1
	v_cndmask_b32_e32 v106, v176, v106, vcc
	v_cmp_lt_i32_e32 vcc, 49, v146
	s_nop 1
	v_cndmask_b32_e32 v90, v176, v90, vcc
	v_cmp_lt_i32_e32 vcc, 18, v146
	s_nop 1
	v_cndmask_b32_e32 v107, v176, v107, vcc
	v_cmp_lt_i32_e32 vcc, 50, v146
	s_nop 1
	v_cndmask_b32_e32 v91, v176, v91, vcc
	v_cmp_lt_i32_e32 vcc, 23, v146
	s_nop 1
	v_cndmask_b32_e32 v108, v176, v108, vcc
	v_cmp_lt_i32_e32 vcc, 55, v146
	s_nop 1
	v_cndmask_b32_e32 v92, v176, v92, vcc
	v_cmp_lt_i32_e32 vcc, 24, v146
	s_nop 1
	v_cndmask_b32_e32 v109, v176, v109, vcc
	v_cmp_lt_i32_e32 vcc, 56, v146
	s_nop 1
	v_cndmask_b32_e32 v93, v176, v93, vcc
	v_cmp_lt_i32_e32 vcc, 25, v146
	s_nop 1
	v_cndmask_b32_e32 v110, v176, v110, vcc
	v_cmp_lt_i32_e32 vcc, 57, v146
	s_nop 1
	v_cndmask_b32_e32 v94, v176, v94, vcc
	v_cmp_lt_i32_e32 vcc, 26, v146
	s_nop 1
	v_cndmask_b32_e32 v111, v176, v111, vcc
	v_cmp_lt_i32_e32 vcc, 58, v146
	s_nop 1
	v_cndmask_b32_e32 v95, v176, v95, vcc
; DI float xhalf(float v) { return __shfl_xor(v, 32); }
; DI float fexp2(float x) { return __builtin_amdgcn_exp2f(x); }
; #define DF_VLD(VF, VOFF, H) do { _Pragma("unroll") for (int d2 = 0; d2 < 2; ++d2) { LAS unsigned char* vb_ = lds3 + (VOFF) + (2 * (H) + d2) * 4096; VF[2 * d2] = vfrag(vb_); VF[2 * d2 + 1] = vfrag(vb_ + 1024); } } while (0)
; #define DF_PVM(VF, P0, P1, H) do { _Pragma("unroll") for (int d2 = 0; d2 < 2; ++d2) { o[2 * (H) + d2] = mfma32(VF[2 * d2], P0, o[2 * (H) + d2]); o[2 * (H) + d2] = mfma32(VF[2 * d2 + 1], P1, o[2 * (H) + d2]); } } while (0)
; DI void diff_stage(const unsigned char* lds, LAS unsigned char* lds3, int buf, int t, int comp, int q0, int r32, int hi, int vlane, bool skew,
;                    const bf16x8 (&qf)[4], f32x16 (&o)[4], float& m, float& l, bf16x8 (&pp)[4], int& pvo, bool& have_prev) {
;     ...
;     float mx = fmaxf(fmaxf(s0[0], s0[1]), s1[0]);
; #pragma unroll
;     for (int i = 1; i < 15; i += 2) { mx = fmaxf(fmaxf(mx, s0[i + 1]), s0[i + 2 > 15 ? 15 : i + 2]); mx = fmaxf(fmaxf(mx, s1[i]), s1[i + 1]); }
;     mx = fmaxf(mx, s1[15]);
;     mx = fmaxf(mx, xhalf(mx)) * SCL2;
;     if (__any(mx > m + 8.f)) {
;         const float mn = fmaxf(m, mx), al = fexp2(m - mn); l *= al; m = mn;
; #pragma unroll
;         for (int dt = 0; dt < 4; ++dt)
; #pragma unroll
;             for (int i = 0; i < 16; ++i) o[dt][i] *= al;
;     }
;     float sum0 = 0.f, sum1 = 0.f;
; #pragma unroll
;     for (int i = 0; i < 16; ++i) { s0[i] = fexp2(__builtin_fmaf(s0[i], SCL2, -m)); sum0 += s0[i]; s1[i] = fexp2(__builtin_fmaf(s1[i], SCL2, -m)); sum1 += s1[i]; }
;     l += sum0 + sum1;
;     const int vo = buf * DF_STAGE + DF_V + vlane;
;     if (!skew) {
;         const bf16x8 p00 = packP<0>(s0), p01 = packP<1>(s0);
;         DF_VLD(vf, vo, 0); DF_PVM(vf, p00, p01, 0); DF_VLD(vf, vo, 1); DF_PVM(vf, p00, p01, 1);
;         const bf16x8 p10 = packP<0>(s1), p11 = packP<1>(s1);
;         DF_VLD(vf, vo + 2048, 0); DF_PVM(vf, p10, p11, 0); DF_VLD(vf, vo + 2048, 1); DF_PVM(vf, p10, p11, 1);
;     } else { pp[0] = packP<0>(s0); pp[1] = packP<1>(s0); pp[2] = packP<0>(s1); pp[3] = packP<1>(s1); pvo = vo; have_prev = true; }
.Ldf1b_nodiag:
	v_max3_f32 v1, v96, v97, v98
	v_max3_f32 v1, v1, v99, v100
	v_max3_f32 v1, v1, v101, v102
	v_max3_f32 v1, v1, v103, v104
	v_max3_f32 v1, v1, v105, v106
	v_max3_f32 v1, v1, v107, v108
	v_max3_f32 v1, v1, v109, v110
	v_max3_f32 v1, v1, v111, v80
	v_max3_f32 v1, v1, v81, v82
	v_max3_f32 v1, v1, v83, v84
	v_max3_f32 v1, v1, v85, v86
	v_max3_f32 v1, v1, v87, v88
	v_max3_f32 v1, v1, v89, v90
	v_max3_f32 v1, v1, v91, v92
	v_max3_f32 v1, v1, v93, v94
	v_max_f32_e32 v1, v1, v95
	v_mov_b32_e32 v14, v1
	s_nop 1
	v_permlane32_swap_b32_e32 v1, v14
	v_add_f32_e32 v15, 0x41000000, v147
	v_max_f32_e32 v1, v1, v14
	v_mul_f32_e32 v1, 0x3e38aa3b, v1
	v_cmp_gt_f32_e32 vcc, v1, v15
	s_cbranch_vccz .Ldf1b_notrig
	v_max_f32_e32 v1, v1, v1
	v_max_f32_e32 v14, v147, v147
	v_max_f32_e32 v1, v14, v1
	v_sub_f32_e32 v14, v147, v1
	v_exp_f32_e32 v206, v14
	v_mov_b32_e32 v147, v1
	s_mov_b32 s60, 1
	v_mul_f32_e32 v143, v143, v206
.Ldf1b_notrig:
	v_fma_f32 v96, v96, s44, -v147
	v_fma_f32 v97, v97, s44, -v147
	v_exp_f32_e32 v96, v96
	v_exp_f32_e32 v97, v97
	v_fma_f32 v98, v98, s44, -v147
	v_fma_f32 v99, v99, s44, -v147
	v_exp_f32_e32 v98, v98
	v_exp_f32_e32 v99, v99
	v_fma_f32 v100, v100, s44, -v147
	v_fma_f32 v101, v101, s44, -v147
	v_exp_f32_e32 v100, v100
	v_exp_f32_e32 v101, v101
	v_fma_f32 v102, v102, s44, -v147
	v_fma_f32 v103, v103, s44, -v147
	v_exp_f32_e32 v102, v102
	v_exp_f32_e32 v103, v103
	v_fma_f32 v104, v104, s44, -v147
	v_fma_f32 v105, v105, s44, -v147
	v_exp_f32_e32 v104, v104
	v_exp_f32_e32 v105, v105
	v_fma_f32 v106, v106, s44, -v147
	v_fma_f32 v107, v107, s44, -v147
	v_exp_f32_e32 v106, v106
	v_exp_f32_e32 v107, v107
	v_fma_f32 v108, v108, s44, -v147
	v_fma_f32 v109, v109, s44, -v147
	v_exp_f32_e32 v108, v108
	v_exp_f32_e32 v109, v109
	v_fma_f32 v110, v110, s44, -v147
	v_fma_f32 v111, v111, s44, -v147
	v_exp_f32_e32 v110, v110
	v_exp_f32_e32 v111, v111
	v_add_f32_e32 v14, v96, v97
	v_add_f32_e32 v14, v14, v98
	v_add_f32_e32 v14, v14, v99
	v_add_f32_e32 v14, v14, v100
	v_add_f32_e32 v14, v14, v101
	v_add_f32_e32 v14, v14, v102
	v_add_f32_e32 v14, v14, v103
	v_add_f32_e32 v14, v14, v104
	v_add_f32_e32 v14, v14, v105
	v_add_f32_e32 v14, v14, v106
	v_add_f32_e32 v14, v14, v107
	v_add_f32_e32 v14, v14, v108
	v_add_f32_e32 v14, v14, v109
	v_add_f32_e32 v14, v14, v110
	v_add_f32_e32 v14, v14, v111
	v_fma_f32 v80, v80, s44, -v147
	v_fma_f32 v81, v81, s44, -v147
	v_exp_f32_e32 v80, v80
	v_exp_f32_e32 v81, v81
	v_fma_f32 v82, v82, s44, -v147
	v_fma_f32 v83, v83, s44, -v147
	v_exp_f32_e32 v82, v82
	v_exp_f32_e32 v83, v83
	v_fma_f32 v84, v84, s44, -v147
	v_fma_f32 v85, v85, s44, -v147
	v_exp_f32_e32 v84, v84
	v_exp_f32_e32 v85, v85
	v_fma_f32 v86, v86, s44, -v147
	v_fma_f32 v87, v87, s44, -v147
	v_exp_f32_e32 v86, v86
	v_exp_f32_e32 v87, v87
	v_fma_f32 v88, v88, s44, -v147
	v_fma_f32 v89, v89, s44, -v147
	v_exp_f32_e32 v88, v88
	v_exp_f32_e32 v89, v89
	v_fma_f32 v90, v90, s44, -v147
	v_fma_f32 v91, v91, s44, -v147
	v_exp_f32_e32 v90, v90
	v_exp_f32_e32 v91, v91
	v_fma_f32 v92, v92, s44, -v147
	v_fma_f32 v93, v93, s44, -v147
	v_exp_f32_e32 v92, v92
	v_exp_f32_e32 v93, v93
	v_fma_f32 v94, v94, s44, -v147
	v_fma_f32 v95, v95, s44, -v147
	v_exp_f32_e32 v94, v94
	v_exp_f32_e32 v95, v95
	v_add_f32_e32 v15, v80, v81
	v_add_f32_e32 v15, v15, v82
	v_add_f32_e32 v15, v15, v83
	v_add_f32_e32 v15, v15, v84
	v_add_f32_e32 v15, v15, v85
	v_add_f32_e32 v15, v15, v86
	v_add_f32_e32 v15, v15, v87
	v_add_f32_e32 v15, v15, v88
	v_add_f32_e32 v15, v15, v89
	v_add_f32_e32 v15, v15, v90
	v_add_f32_e32 v15, v15, v91
	v_add_f32_e32 v15, v15, v92
	v_add_f32_e32 v15, v15, v93
	v_add_f32_e32 v15, v15, v94
	v_add_f32_e32 v15, v15, v95
	v_add_f32_e32 v14, v14, v15
	v_add_f32_e32 v143, v143, v14
	v_cvt_pk_bf16_f32 v240, v96, v97
	v_cvt_pk_bf16_f32 v241, v98, v99
	v_cvt_pk_bf16_f32 v242, v100, v101
	v_cvt_pk_bf16_f32 v243, v102, v103
	v_cvt_pk_bf16_f32 v244, v104, v105
	v_cvt_pk_bf16_f32 v245, v106, v107
	v_cvt_pk_bf16_f32 v246, v108, v109
	v_cvt_pk_bf16_f32 v247, v110, v111
	v_cvt_pk_bf16_f32 v248, v80, v81
	v_cvt_pk_bf16_f32 v249, v82, v83
	v_cvt_pk_bf16_f32 v250, v84, v85
	v_cvt_pk_bf16_f32 v251, v86, v87
	v_cvt_pk_bf16_f32 v252, v88, v89
	v_cvt_pk_bf16_f32 v253, v90, v91
	v_cvt_pk_bf16_f32 v254, v92, v93
	v_cvt_pk_bf16_f32 v255, v94, v95
	s_mov_b32 s61, 1
	s_branch .Ldf1b_bar

; DI f32x16 mfma32(bf16x8 a, bf16x8 b, f32x16 c) { return __builtin_amdgcn_mfma_f32_32x32x16_bf16(a, b, c, 0, 0, 0); }
; #define DF_VLD(VF, VOFF, H) do { _Pragma("unroll") for (int d2 = 0; d2 < 2; ++d2) { LAS unsigned char* vb_ = lds3 + (VOFF) + (2 * (H) + d2) * 4096; VF[2 * d2] = vfrag(vb_); VF[2 * d2 + 1] = vfrag(vb_ + 1024); } } while (0)
; DI void diff_stage(const unsigned char* lds, LAS unsigned char* lds3, int buf, int t, int comp, int q0, int r32, int hi, int vlane, bool skew,
;                    const bf16x8 (&qf)[4], f32x16 (&o)[4], float& m, float& l, bf16x8 (&pp)[4], int& pvo, bool& have_prev) {
;     const int k0 = 64 * t;
;     if (k0 > q0 + 31) return;
;     const unsigned char* sb = lds + buf * DF_STAGE + comp * DF_K2 + r32 * 128; const int ke16 = (hi ^ ((r32 >> 1) & 7)) * 16;
;     bf16x8 vf[4];
;     if (skew && have_prev) {
; #pragma unroll
;         for (int sub = 0; sub < 2; ++sub) { DF_VLD(vf, pvo + sub * 2048, 0); DF_PVM(vf, pp[2 * sub], pp[2 * sub + 1], 0); DF_VLD(vf, pvo + sub * 2048, 1); DF_PVM(vf, pp[2 * sub], pp[2 * sub + 1], 1); }
;     }
;     f32x16 s0, s1;
; #pragma unroll
;     for (int i = 0; i < 16; ++i) { s0[i] = 0.f; s1[i] = 0.f; }
;     {
;         bf16x8 k0f[4], k1f[4];
; #pragma unroll
;         for (int c = 0; c < 4; ++c) { k0f[c] = *(const bf16x8*)(sb + ((32 * c) ^ ke16)); k1f[c] = *(const bf16x8*)(sb + 32 * 128 + ((32 * c) ^ ke16)); }
; #pragma unroll
;         for (int c = 0; c < 4; ++c) { s0 = mfma32(k0f[c], qf[c], s0); s1 = mfma32(k1f[c], qf[c], s1); }
;     }
;     if (k0 + 63 > q0) {
;         const int dq = q0 + r32 - k0 - 4 * hi;
; #pragma unroll
;         for (int i = 0; i < 16; ++i) { const int ci = (i & 3) + 8 * (i >> 2); s0[i] = (ci > dq) ? -INFINITY : s0[i]; s1[i] = (ci + 32 > dq) ? -INFINITY : s1[i]; }
;     }
; DI void diff_unit(const Args& A, const bf16_t* QKV, bf16_t* ATT, unsigned char* lds, LAS unsigned char* lds3, int b, int head, int qb, int tid, int wid, int lane) {
;     ...
;     for (int t = 0; t < nst; ++t) {
;         { const int tl = (t + 2 < nst) ? t + 2 : nst - 1; DF_DMA(tl, (t + 2) & 3); }
;         diff_stage(lds, lds3, t & 3, t, comp, q0, r32, hi, vlane, skew, qf, o, m, l, pp, pvo, have_prev);
.Ldf1a_loop:
	s_sub_i32 s71, s8, 63
	s_cmp_gt_u32 s71, s53
	s_cbranch_scc1 .Ldf1a_skip
	s_and_b32 s55, s11, 0x18000
	v_add_u32_e32 v2, s55, v160
	v_add_u32_e32 v3, v2, v161
	v_add_u32_e32 v4, v2, v162
	v_add_u32_e32 v5, v2, v163
	v_add_u32_e32 v2, v2, v164
	ds_read_b128 v[208:211], v3
	ds_read_b128 v[212:215], v3 offset:4096
	ds_read_b128 v[216:219], v4
	ds_read_b128 v[220:223], v4 offset:4096
	ds_read_b128 v[224:227], v5
	ds_read_b128 v[228:231], v5 offset:4096
	ds_read_b128 v[232:235], v2
	ds_read_b128 v[236:239], v2 offset:4096
	s_mov_b32 m0, s67
	s_nop 0
	global_load_lds_dwordx4 v156, s[64:65]
	s_mov_b32 m0, s68
	s_nop 0
	global_load_lds_dwordx4 v159, s[64:65]
	s_mov_b32 m0, s69
	s_nop 0
	global_load_lds_dwordx4 v157, s[64:65]
	s_mov_b32 m0, s70
	s_nop 0
	global_load_lds_dwordx4 v158, s[64:65]
	v_add_u32_e32 v6, s55, v165
	s_waitcnt lgkmcnt(7)
	v_mfma_f32_32x32x16_bf16 v[96:111], v[208:211], v[124:127], 0
	s_waitcnt lgkmcnt(6)
	v_mfma_f32_32x32x16_bf16 v[80:95], v[212:215], v[124:127], 0
	s_waitcnt lgkmcnt(5)
	v_mfma_f32_32x32x16_bf16 v[96:111], v[216:219], v[120:123], v[96:111]
	s_waitcnt lgkmcnt(4)
	v_mfma_f32_32x32x16_bf16 v[80:95], v[220:223], v[120:123], v[80:95]
	s_waitcnt lgkmcnt(3)
	v_mfma_f32_32x32x16_bf16 v[96:111], v[224:227], v[116:119], v[96:111]
	s_waitcnt lgkmcnt(2)
	v_mfma_f32_32x32x16_bf16 v[80:95], v[228:231], v[116:119], v[80:95]
	s_waitcnt lgkmcnt(1)
	v_mfma_f32_32x32x16_bf16 v[96:111], v[232:235], v[112:115], v[96:111]
	s_waitcnt lgkmcnt(0)
	v_mfma_f32_32x32x16_bf16 v[80:95], v[236:239], v[112:115], v[80:95]
	ds_read_b64_tr_b16 v[208:209], v6 offset:16384
	ds_read_b64_tr_b16 v[210:211], v6 offset:16896
	ds_read_b64_tr_b16 v[212:213], v6 offset:17408
	ds_read_b64_tr_b16 v[214:215], v6 offset:17920
	ds_read_b64_tr_b16 v[216:217], v6 offset:20480
	ds_read_b64_tr_b16 v[218:219], v6 offset:20992
	ds_read_b64_tr_b16 v[220:221], v6 offset:21504
	ds_read_b64_tr_b16 v[222:223], v6 offset:22016
	ds_read_b64_tr_b16 v[224:225], v6 offset:24576
	ds_read_b64_tr_b16 v[226:227], v6 offset:25088
	ds_read_b64_tr_b16 v[228:229], v6 offset:25600
	ds_read_b64_tr_b16 v[230:231], v6 offset:26112
	s_cmp_le_u32 s8, s7
	s_cbranch_scc1 .Ldf1a_nodiag
	s_nop 7
	v_cmp_lt_i32_e32 vcc, -1, v146
	s_nop 1
	v_cndmask_b32_e32 v96, v176, v96, vcc
	v_cmp_lt_i32_e32 vcc, 31, v146
	s_nop 1
	v_cndmask_b32_e32 v80, v176, v80, vcc
	v_cmp_lt_i32_e32 vcc, 0, v146
	s_nop 1
	v_cndmask_b32_e32 v97, v176, v97, vcc
	v_cmp_lt_i32_e32 vcc, 32, v146
	s_nop 1
	v_cndmask_b32_e32 v81, v176, v81, vcc
	v_cmp_lt_i32_e32 vcc, 1, v146
	s_nop 1
	v_cndmask_b32_e32 v98, v176, v98, vcc
	v_cmp_lt_i32_e32 vcc, 33, v146
	s_nop 1
	v_cndmask_b32_e32 v82, v176, v82, vcc
	v_cmp_lt_i32_e32 vcc, 2, v146
	s_nop 1
	v_cndmask_b32_e32 v99, v176, v99, vcc
	v_cmp_lt_i32_e32 vcc, 34, v146
	s_nop 1
	v_cndmask_b32_e32 v83, v176, v83, vcc
	v_cmp_lt_i32_e32 vcc, 7, v146
	s_nop 1
	v_cndmask_b32_e32 v100, v176, v100, vcc
	v_cmp_lt_i32_e32 vcc, 39, v146
	s_nop 1
	v_cndmask_b32_e32 v84, v176, v84, vcc
	v_cmp_lt_i32_e32 vcc, 8, v146
	s_nop 1
	v_cndmask_b32_e32 v101, v176, v101, vcc
	v_cmp_lt_i32_e32 vcc, 40, v146
	s_nop 1
	v_cndmask_b32_e32 v85, v176, v85, vcc
	v_cmp_lt_i32_e32 vcc, 9, v146
	s_nop 1
	v_cndmask_b32_e32 v102, v176, v102, vcc
	v_cmp_lt_i32_e32 vcc, 41, v146
	s_nop 1
	v_cndmask_b32_e32 v86, v176, v86, vcc
	v_cmp_lt_i32_e32 vcc, 10, v146
	s_nop 1
	v_cndmask_b32_e32 v103, v176, v103, vcc
	v_cmp_lt_i32_e32 vcc, 42, v146
	s_nop 1
	v_cndmask_b32_e32 v87, v176, v87, vcc
	v_cmp_lt_i32_e32 vcc, 15, v146
	s_nop 1
	v_cndmask_b32_e32 v104, v176, v104, vcc
	v_cmp_lt_i32_e32 vcc, 47, v146
	s_nop 1
	v_cndmask_b32_e32 v88, v176, v88, vcc
	v_cmp_lt_i32_e32 vcc, 16, v146
	s_nop 1
	v_cndmask_b32_e32 v105, v176, v105, vcc
	v_cmp_lt_i32_e32 vcc, 48, v146
	s_nop 1
	v_cndmask_b32_e32 v89, v176, v89, vcc
	v_cmp_lt_i32_e32 vcc, 17, v146
	s_nop 1
	v_cndmask_b32_e32 v106, v176, v106, vcc
	v_cmp_lt_i32_e32 vcc, 49, v146
	s_nop 1
	v_cndmask_b32_e32 v90, v176, v90, vcc
	v_cmp_lt_i32_e32 vcc, 18, v146
	s_nop 1
	v_cndmask_b32_e32 v107, v176, v107, vcc
	v_cmp_lt_i32_e32 vcc, 50, v146
	s_nop 1
	v_cndmask_b32_e32 v91, v176, v91, vcc
	v_cmp_lt_i32_e32 vcc, 23, v146
	s_nop 1
	v_cndmask_b32_e32 v108, v176, v108, vcc
	v_cmp_lt_i32_e32 vcc, 55, v146
	s_nop 1
	v_cndmask_b32_e32 v92, v176, v92, vcc
	v_cmp_lt_i32_e32 vcc, 24, v146
	s_nop 1
	v_cndmask_b32_e32 v109, v176, v109, vcc
	v_cmp_lt_i32_e32 vcc, 56, v146
	s_nop 1
	v_cndmask_b32_e32 v93, v176, v93, vcc
	v_cmp_lt_i32_e32 vcc, 25, v146
	s_nop 1
	v_cndmask_b32_e32 v110, v176, v110, vcc
	v_cmp_lt_i32_e32 vcc, 57, v146
	s_nop 1
	v_cndmask_b32_e32 v94, v176, v94, vcc
	v_cmp_lt_i32_e32 vcc, 26, v146
	s_nop 1
	v_cndmask_b32_e32 v111, v176, v111, vcc
	v_cmp_lt_i32_e32 vcc, 58, v146
	s_nop 1
	v_cndmask_b32_e32 v95, v176, v95, vcc
; DI float xhalf(float v) { return __shfl_xor(v, 32); }
; DI float fexp2(float x) { return __builtin_amdgcn_exp2f(x); }
; DI void diff_stage(const unsigned char* lds, LAS unsigned char* lds3, int buf, int t, int comp, int q0, int r32, int hi, int vlane, bool skew,
;                    const bf16x8 (&qf)[4], f32x16 (&o)[4], float& m, float& l, bf16x8 (&pp)[4], int& pvo, bool& have_prev) {
;     ...
;     float mx = fmaxf(fmaxf(s0[0], s0[1]), s1[0]);
; #pragma unroll
;     for (int i = 1; i < 15; i += 2) { mx = fmaxf(fmaxf(mx, s0[i + 1]), s0[i + 2 > 15 ? 15 : i + 2]); mx = fmaxf(fmaxf(mx, s1[i]), s1[i + 1]); }
;     mx = fmaxf(mx, s1[15]);
;     mx = fmaxf(mx, xhalf(mx)) * SCL2;
;     if (__any(mx > m + 8.f)) {
;         const float mn = fmaxf(m, mx), al = fexp2(m - mn); l *= al; m = mn;
; #pragma unroll
;         for (int dt = 0; dt < 4; ++dt)
; #pragma unroll
;             for (int i = 0; i < 16; ++i) o[dt][i] *= al;
;     }
.Ldf1a_nodiag:
	v_max3_f32 v1, v96, v97, v98
	v_max3_f32 v1, v1, v99, v100
	v_max3_f32 v1, v1, v101, v102
	v_max3_f32 v1, v1, v103, v104
	v_max3_f32 v1, v1, v105, v106
	v_max3_f32 v1, v1, v107, v108
	v_max3_f32 v1, v1, v109, v110
	v_max3_f32 v1, v1, v111, v80
	v_max3_f32 v1, v1, v81, v82
	v_max3_f32 v1, v1, v83, v84
	v_max3_f32 v1, v1, v85, v86
	v_max3_f32 v1, v1, v87, v88
	v_max3_f32 v1, v1, v89, v90
	v_max3_f32 v1, v1, v91, v92
	v_max3_f32 v1, v1, v93, v94
	v_max_f32_e32 v1, v1, v95
	v_mov_b32_e32 v14, v1
	s_nop 1
	v_permlane32_swap_b32_e32 v1, v14
	v_add_f32_e32 v15, 0x41000000, v147
	v_max_f32_e32 v1, v1, v14
	v_mul_f32_e32 v1, 0x3e38aa3b, v1
	v_cmp_gt_f32_e32 vcc, v1, v15
	s_cbranch_vccz .Ldf1a_notrig
	v_max_f32_e32 v1, v1, v1
	v_max_f32_e32 v14, v147, v147
	v_max_f32_e32 v1, v14, v1
	v_sub_f32_e32 v14, v147, v1
	v_exp_f32_e32 v206, v14
	v_mov_b32_e32 v147, v1
	v_pk_mul_f32 v[78:79], v[78:79], v[206:207] op_sel_hi:[1,0]
	v_pk_mul_f32 v[76:77], v[76:77], v[206:207] op_sel_hi:[1,0]
	v_pk_mul_f32 v[74:75], v[74:75], v[206:207] op_sel_hi:[1,0]
	v_pk_mul_f32 v[72:73], v[72:73], v[206:207] op_sel_hi:[1,0]
	v_pk_mul_f32 v[70:71], v[70:71], v[206:207] op_sel_hi:[1,0]
	v_pk_mul_f32 v[68:69], v[68:69], v[206:207] op_sel_hi:[1,0]
	v_pk_mul_f32 v[66:67], v[66:67], v[206:207] op_sel_hi:[1,0]
	v_pk_mul_f32 v[64:65], v[64:65], v[206:207] op_sel_hi:[1,0]
	v_pk_mul_f32 v[62:63], v[62:63], v[206:207] op_sel_hi:[1,0]
	v_pk_mul_f32 v[60:61], v[60:61], v[206:207] op_sel_hi:[1,0]
	v_pk_mul_f32 v[58:59], v[58:59], v[206:207] op_sel_hi:[1,0]
	v_pk_mul_f32 v[56:57], v[56:57], v[206:207] op_sel_hi:[1,0]
	v_pk_mul_f32 v[54:55], v[54:55], v[206:207] op_sel_hi:[1,0]
	v_pk_mul_f32 v[52:53], v[52:53], v[206:207] op_sel_hi:[1,0]
	v_pk_mul_f32 v[50:51], v[50:51], v[206:207] op_sel_hi:[1,0]
	v_pk_mul_f32 v[48:49], v[48:49], v[206:207] op_sel_hi:[1,0]
	v_pk_mul_f32 v[46:47], v[46:47], v[206:207] op_sel_hi:[1,0]
	v_pk_mul_f32 v[44:45], v[44:45], v[206:207] op_sel_hi:[1,0]
	v_pk_mul_f32 v[42:43], v[42:43], v[206:207] op_sel_hi:[1,0]
	v_pk_mul_f32 v[40:41], v[40:41], v[206:207] op_sel_hi:[1,0]
	v_pk_mul_f32 v[38:39], v[38:39], v[206:207] op_sel_hi:[1,0]
	v_pk_mul_f32 v[36:37], v[36:37], v[206:207] op_sel_hi:[1,0]
	v_pk_mul_f32 v[34:35], v[34:35], v[206:207] op_sel_hi:[1,0]
	v_pk_mul_f32 v[32:33], v[32:33], v[206:207] op_sel_hi:[1,0]
	v_pk_mul_f32 v[30:31], v[30:31], v[206:207] op_sel_hi:[1,0]
	v_pk_mul_f32 v[28:29], v[28:29], v[206:207] op_sel_hi:[1,0]
	v_pk_mul_f32 v[26:27], v[26:27], v[206:207] op_sel_hi:[1,0]
	v_pk_mul_f32 v[24:25], v[24:25], v[206:207] op_sel_hi:[1,0]
	v_pk_mul_f32 v[22:23], v[22:23], v[206:207] op_sel_hi:[1,0]
	v_pk_mul_f32 v[20:21], v[20:21], v[206:207] op_sel_hi:[1,0]
	v_pk_mul_f32 v[18:19], v[18:19], v[206:207] op_sel_hi:[1,0]
	v_pk_mul_f32 v[16:17], v[16:17], v[206:207] op_sel_hi:[1,0]
	v_mul_f32_e32 v143, v143, v206
; DI float fexp2(float x) { return __builtin_amdgcn_exp2f(x); }
; #define DF_VLD(VF, VOFF, H) do { _Pragma("unroll") for (int d2 = 0; d2 < 2; ++d2) { LAS unsigned char* vb_ = lds3 + (VOFF) + (2 * (H) + d2) * 4096; VF[2 * d2] = vfrag(vb_); VF[2 * d2 + 1] = vfrag(vb_ + 1024); } } while (0)
; #define DF_PVM(VF, P0, P1, H) do { _Pragma("unroll") for (int d2 = 0; d2 < 2; ++d2) { o[2 * (H) + d2] = mfma32(VF[2 * d2], P0, o[2 * (H) + d2]); o[2 * (H) + d2] = mfma32(VF[2 * d2 + 1], P1, o[2 * (H) + d2]); } } while (0)
; DI void diff_stage(const unsigned char* lds, LAS unsigned char* lds3, int buf, int t, int comp, int q0, int r32, int hi, int vlane, bool skew,
;                    const bf16x8 (&qf)[4], f32x16 (&o)[4], float& m, float& l, bf16x8 (&pp)[4], int& pvo, bool& have_prev) {
;     ...
;     float sum0 = 0.f, sum1 = 0.f;
; #pragma unroll
;     for (int i = 0; i < 16; ++i) { s0[i] = fexp2(__builtin_fmaf(s0[i], SCL2, -m)); sum0 += s0[i]; s1[i] = fexp2(__builtin_fmaf(s1[i], SCL2, -m)); sum1 += s1[i]; }
;     l += sum0 + sum1;
;     const int vo = buf * DF_STAGE + DF_V + vlane;
;     if (!skew) {
;         const bf16x8 p00 = packP<0>(s0), p01 = packP<1>(s0);
;         DF_VLD(vf, vo, 0); DF_PVM(vf, p00, p01, 0); DF_VLD(vf, vo, 1); DF_PVM(vf, p00, p01, 1);
;         const bf16x8 p10 = packP<0>(s1), p11 = packP<1>(s1);
;         DF_VLD(vf, vo + 2048, 0); DF_PVM(vf, p10, p11, 0); DF_VLD(vf, vo + 2048, 1); DF_PVM(vf, p10, p11, 1);
.Ldf1a_notrig:
	v_fma_f32 v96, v96, s44, -v147
	v_fma_f32 v97, v97, s44, -v147
	v_exp_f32_e32 v96, v96
	v_exp_f32_e32 v97, v97
	v_fma_f32 v98, v98, s44, -v147
	v_fma_f32 v99, v99, s44, -v147
	v_exp_f32_e32 v98, v98
	v_exp_f32_e32 v99, v99
	v_fma_f32 v100, v100, s44, -v147
	v_fma_f32 v101, v101, s44, -v147
	v_exp_f32_e32 v100, v100
	v_exp_f32_e32 v101, v101
	v_fma_f32 v102, v102, s44, -v147
	v_fma_f32 v103, v103, s44, -v147
	v_exp_f32_e32 v102, v102
	v_exp_f32_e32 v103, v103
	v_fma_f32 v104, v104, s44, -v147
	v_fma_f32 v105, v105, s44, -v147
	v_exp_f32_e32 v104, v104
	v_exp_f32_e32 v105, v105
	v_fma_f32 v106, v106, s44, -v147
	v_fma_f32 v107, v107, s44, -v147
	v_exp_f32_e32 v106, v106
	v_exp_f32_e32 v107, v107
	v_fma_f32 v108, v108, s44, -v147
	v_fma_f32 v109, v109, s44, -v147
	v_exp_f32_e32 v108, v108
	v_exp_f32_e32 v109, v109
	v_fma_f32 v110, v110, s44, -v147
	v_fma_f32 v111, v111, s44, -v147
	v_exp_f32_e32 v110, v110
	v_exp_f32_e32 v111, v111
	v_add_f32_e32 v14, v96, v97
	v_add_f32_e32 v14, v14, v98
	v_add_f32_e32 v14, v14, v99
	v_add_f32_e32 v14, v14, v100
	v_add_f32_e32 v14, v14, v101
	v_add_f32_e32 v14, v14, v102
	v_add_f32_e32 v14, v14, v103
	v_add_f32_e32 v14, v14, v104
	v_add_f32_e32 v14, v14, v105
	v_add_f32_e32 v14, v14, v106
	v_add_f32_e32 v14, v14, v107
	v_add_f32_e32 v14, v14, v108
	v_add_f32_e32 v14, v14, v109
	v_add_f32_e32 v14, v14, v110
	v_add_f32_e32 v14, v14, v111
	v_fma_f32 v80, v80, s44, -v147
	v_fma_f32 v81, v81, s44, -v147
	v_exp_f32_e32 v80, v80
	v_exp_f32_e32 v81, v81
	v_fma_f32 v82, v82, s44, -v147
	v_fma_f32 v83, v83, s44, -v147
	v_exp_f32_e32 v82, v82
	v_exp_f32_e32 v83, v83
	v_fma_f32 v84, v84, s44, -v147
	v_fma_f32 v85, v85, s44, -v147
	v_exp_f32_e32 v84, v84
	v_exp_f32_e32 v85, v85
	v_fma_f32 v86, v86, s44, -v147
	v_fma_f32 v87, v87, s44, -v147
	v_exp_f32_e32 v86, v86
	v_exp_f32_e32 v87, v87
	v_fma_f32 v88, v88, s44, -v147
	v_fma_f32 v89, v89, s44, -v147
	v_exp_f32_e32 v88, v88
	v_exp_f32_e32 v89, v89
	v_fma_f32 v90, v90, s44, -v147
	v_fma_f32 v91, v91, s44, -v147
	v_exp_f32_e32 v90, v90
	v_exp_f32_e32 v91, v91
	v_fma_f32 v92, v92, s44, -v147
	v_fma_f32 v93, v93, s44, -v147
	v_exp_f32_e32 v92, v92
	v_exp_f32_e32 v93, v93
	v_fma_f32 v94, v94, s44, -v147
	v_fma_f32 v95, v95, s44, -v147
	v_exp_f32_e32 v94, v94
	v_exp_f32_e32 v95, v95
	v_add_f32_e32 v15, v80, v81
	v_add_f32_e32 v15, v15, v82
	v_add_f32_e32 v15, v15, v83
	v_add_f32_e32 v15, v15, v84
	v_add_f32_e32 v15, v15, v85
	v_add_f32_e32 v15, v15, v86
	v_add_f32_e32 v15, v15, v87
	v_add_f32_e32 v15, v15, v88
	v_add_f32_e32 v15, v15, v89
	v_add_f32_e32 v15, v15, v90
	v_add_f32_e32 v15, v15, v91
	v_add_f32_e32 v15, v15, v92
	v_add_f32_e32 v15, v15, v93
	v_add_f32_e32 v15, v15, v94
	v_add_f32_e32 v15, v15, v95
	v_add_f32_e32 v14, v14, v15
	v_add_f32_e32 v143, v143, v14
	v_cvt_pk_bf16_f32 v240, v96, v97
	v_cvt_pk_bf16_f32 v241, v98, v99
	v_cvt_pk_bf16_f32 v242, v100, v101
	v_cvt_pk_bf16_f32 v243, v102, v103
	v_cvt_pk_bf16_f32 v244, v104, v105
	v_cvt_pk_bf16_f32 v245, v106, v107
	v_cvt_pk_bf16_f32 v246, v108, v109
	v_cvt_pk_bf16_f32 v247, v110, v111
	v_cvt_pk_bf16_f32 v248, v80, v81
	v_cvt_pk_bf16_f32 v249, v82, v83
	v_cvt_pk_bf16_f32 v250, v84, v85
	v_cvt_pk_bf16_f32 v251, v86, v87
	v_cvt_pk_bf16_f32 v252, v88, v89
	v_cvt_pk_bf16_f32 v253, v90, v91
	v_cvt_pk_bf16_f32 v254, v92, v93
	v_cvt_pk_bf16_f32 v255, v94, v95
	s_nop 1
	s_waitcnt lgkmcnt(10)
	v_mfma_f32_32x32x16_bf16 v[64:79], v[208:211], v[240:243], v[64:79]
	ds_read_b64_tr_b16 v[232:233], v6 offset:28672
	ds_read_b64_tr_b16 v[234:235], v6 offset:29184
	s_waitcnt lgkmcnt(10)
	v_mfma_f32_32x32x16_bf16 v[64:79], v[212:215], v[244:247], v[64:79]
	ds_read_b64_tr_b16 v[236:237], v6 offset:29696
	ds_read_b64_tr_b16 v[238:239], v6 offset:30208
	s_waitcnt lgkmcnt(10)
	v_mfma_f32_32x32x16_bf16 v[48:63], v[216:219], v[240:243], v[48:63]
	ds_read_b64_tr_b16 v[208:209], v6 offset:18432
	ds_read_b64_tr_b16 v[210:211], v6 offset:18944
	s_waitcnt lgkmcnt(10)
	v_mfma_f32_32x32x16_bf16 v[48:63], v[220:223], v[244:247], v[48:63]
	ds_read_b64_tr_b16 v[212:213], v6 offset:19456
	ds_read_b64_tr_b16 v[214:215], v6 offset:19968
	s_waitcnt lgkmcnt(10)
	v_mfma_f32_32x32x16_bf16 v[32:47], v[224:227], v[240:243], v[32:47]
	ds_read_b64_tr_b16 v[216:217], v6 offset:22528
	ds_read_b64_tr_b16 v[218:219], v6 offset:23040
	s_waitcnt lgkmcnt(10)
	v_mfma_f32_32x32x16_bf16 v[32:47], v[228:231], v[244:247], v[32:47]
	ds_read_b64_tr_b16 v[220:221], v6 offset:23552
	ds_read_b64_tr_b16 v[222:223], v6 offset:24064
	s_waitcnt lgkmcnt(10)
	v_mfma_f32_32x32x16_bf16 v[16:31], v[232:235], v[240:243], v[16:31]
	ds_read_b64_tr_b16 v[224:225], v6 offset:26624
	ds_read_b64_tr_b16 v[226:227], v6 offset:27136
	s_waitcnt lgkmcnt(10)
	v_mfma_f32_32x32x16_bf16 v[16:31], v[236:239], v[244:247], v[16:31]
	ds_read_b64_tr_b16 v[228:229], v6 offset:27648
	ds_read_b64_tr_b16 v[230:231], v6 offset:28160
	s_waitcnt lgkmcnt(10)
	v_mfma_f32_32x32x16_bf16 v[64:79], v[208:211], v[248:251], v[64:79]
	ds_read_b64_tr_b16 v[232:233], v6 offset:30720
	ds_read_b64_tr_b16 v[234:235], v6 offset:31232
	s_waitcnt lgkmcnt(10)
	v_mfma_f32_32x32x16_bf16 v[64:79], v[212:215], v[252:255], v[64:79]
	ds_read_b64_tr_b16 v[236:237], v6 offset:31744
	ds_read_b64_tr_b16 v[238:239], v6 offset:32256
	s_waitcnt lgkmcnt(10)
	v_mfma_f32_32x32x16_bf16 v[48:63], v[216:219], v[248:251], v[48:63]
	s_waitcnt lgkmcnt(8)
	v_mfma_f32_32x32x16_bf16 v[48:63], v[220:223], v[252:255], v[48:63]
	s_waitcnt lgkmcnt(6)
	v_mfma_f32_32x32x16_bf16 v[32:47], v[224:227], v[248:251], v[32:47]
	s_waitcnt lgkmcnt(4)
	v_mfma_f32_32x32x16_bf16 v[32:47], v[228:231], v[252:255], v[32:47]
	s_waitcnt lgkmcnt(2)
	v_mfma_f32_32x32x16_bf16 v[16:31], v[232:235], v[248:251], v[16:31]
	s_waitcnt lgkmcnt(0)
	v_mfma_f32_32x32x16_bf16 v[16:31], v[236:239], v[252:255], v[16:31]
	s_branch .Ldf1a_bar

; #define DF_DMA(t, bufi) do { const bf16_t* sb_ = sbase + (size_t)(64 * (t)) * QKVW; const unsigned base_ = (unsigned)__builtin_amdgcn_readfirstlane(ldsb + (bufi) * DF_STAGE); \
;         glds16s(sb_, oK, base_ + dK); glds16s(sb_, oK + 128u, base_ + DF_K2 + dK); glds16s(sb_, oV0, base_ + dV0); glds16s(sb_, oV1, base_ + dV1); } while (0)
; DI void diff_unit(const Args& A, const bf16_t* QKV, bf16_t* ATT, unsigned char* lds, LAS unsigned char* lds3, int b, int head, int qb, int tid, int wid, int lane) {
;     const int r32 = lane & 31, hi = lane >> 5, comp = wid >> 2, wq = wid & 3;
;     const size_t rowbase = (size_t)b * SEQ;
;     const int q0 = qb * 128 + wq * 32;
;     const int qcol = 1536 + head * 128 + comp * 64;
;     bf16x8 qf[4];
; #pragma unroll
;     for (int c = 0; c < 4; ++c) qf[c] = *(const bf16x8*)(QKV + (rowbase + q0 + r32) * QKVW + qcol + 16 * c + 8 * hi);
;     f32x16 o[4];
; #pragma unroll
;     for (int t = 0; t < 4; ++t)
; #pragma unroll
;         for (int i = 0; i < 16; ++i) o[t][i] = 0.f;
;     float m = -INFINITY, l = 0.f;
;     const int nst = 2 * (qb + 1);
;     const unsigned ldsb = (unsigned)(uintptr_t)lds3;
;     const int kkey = 8 * wid + (lane >> 3), kch = (lane & 7) ^ ((kkey >> 1) & 7);
;     const int vi0 = 2 * wid, vi1 = 2 * wid + 1;
;     const bf16_t* sbase = QKV + rowbase * QKVW + head * 128;
;     const unsigned oK = (unsigned)((kkey * QKVW + 2048 + kch * 8) * 2);
;     const unsigned oV0 = (unsigned)(((16 * (vi0 & 3) + (lane >> 2)) * QKVW + 2560 + ((vi0 >> 2) * 4 + (lane & 3)) * 8) * 2);
;     const unsigned oV1 = (unsigned)(((16 * (vi1 & 3) + (lane >> 2)) * QKVW + 2560 + ((vi1 >> 2) * 4 + (lane & 3)) * 8) * 2);
;     const unsigned dK = (unsigned)__builtin_amdgcn_readfirstlane(wid * 1024);
;     const unsigned dV0 = (unsigned)__builtin_amdgcn_readfirstlane(DF_V + (vi0 >> 2) * 4096 + (vi0 & 3) * 1024), dV1 = (unsigned)__builtin_amdgcn_readfirstlane(DF_V + (vi1 >> 2) * 4096 + (vi1 & 3) * 1024);
;     ...
;     DF_DMA(0, 0); DF_DMA(1, 1);
;     asm volatile("" : "+v"(qf[0]), "+v"(qf[1]), "+v"(qf[2]), "+v"(qf[3]));
;     DF_WAITBAR(4);
;     const int vlane = (4 * hi + ((lane & 15) >> 2)) * 64 + ((lane >> 4) & 1) * 32 + (lane & 3) * 8;
;     const bool skew = false;
;     bf16x8 pp[4]; { const bf16x8 z8 = {0, 0, 0, 0, 0, 0, 0, 0}; pp[0] = z8; pp[1] = z8; pp[2] = z8; pp[3] = z8; } int pvo = vlane; bool have_prev = false;
.LBB0_291:
	s_lshl_b32 s52, s49, 7
	s_or_b32 s10, s52, s34
	v_or_b32_e32 v1, s10, v129
	v_or_b32_e32 v154, s26, v1
	v_mov_b64_e32 v[2:3], s[12:13]
	v_mad_u64_u32 v[2:3], s[50:51], v154, s43, v[2:3]
	v_mad_i32_i24 v3, s27, v169, v3
	v_lshl_add_u64 v[2:3], s[28:29], 1, v[2:3]
	v_mov_b32_e32 v143, v0
	v_lshl_add_u64 v[2:3], v[2:3], 0, v[142:143]
	s_barrier
	global_load_dwordx4 v[112:115], v[2:3], off offset:3168
	global_load_dwordx4 v[116:119], v[2:3], off offset:3136
	global_load_dwordx4 v[120:123], v[2:3], off offset:3104
	global_load_dwordx4 v[124:127], v[2:3], off offset:3072
	s_lshl_b32 s22, s33, 10
	v_add_u32_e32 v183, s52, v168
	s_mov_b32 s52, m0
	s_mov_b32 m0, s22
	s_nop 0
	global_load_lds_dwordx4 v156, s[24:25]
	s_mov_b32 m0, s52
	s_add_i32 s28, s22, 0x2000
	s_mov_b32 s52, m0
	s_mov_b32 m0, s28
	s_nop 0
	global_load_lds_dwordx4 v159, s[24:25]
	s_mov_b32 m0, s52
	s_add_i32 s53, s22, 0x8000
	s_mov_b32 s52, m0
	s_mov_b32 m0, s36
	s_nop 0
	global_load_lds_dwordx4 v157, s[24:25]
	s_mov_b32 m0, s52
	s_add_i32 s54, s22, 0xa000
	s_mov_b32 s52, m0
	s_mov_b32 m0, s37
	s_nop 0
	global_load_lds_dwordx4 v158, s[24:25]
	s_mov_b32 m0, s52
	s_add_i32 s50, s36, 0x8000
	s_mov_b32 s52, m0
	s_mov_b32 m0, s53
	s_nop 0
	global_load_lds_dwordx4 v156, s[30:31]
	s_mov_b32 m0, s52
	s_add_i32 s51, s37, 0x8000
	s_mov_b32 s52, m0
	s_mov_b32 m0, s54
	s_nop 0
	global_load_lds_dwordx4 v159, s[30:31]
	s_mov_b32 m0, s52
	v_mov_b32_e32 v14, v0
	s_mov_b32 s52, m0
	s_mov_b32 m0, s50
	s_nop 0
	global_load_lds_dwordx4 v157, s[30:31]
	s_mov_b32 m0, s52
	v_mov_b32_e32 v15, v0
	s_mov_b32 s50, m0
	s_mov_b32 m0, s51
	s_nop 0
	global_load_lds_dwordx4 v158, s[30:31]
	s_mov_b32 m0, s50
	s_lshl_b32 s11, s49, 1
	v_mov_b32_e32 v1, v0
	v_mov_b32_e32 v2, v0
	v_mov_b32_e32 v3, v0
	v_mov_b32_e32 v4, v0
	v_mov_b32_e32 v5, v0
	v_mov_b32_e32 v6, v0
	v_mov_b32_e32 v7, v0
	v_mov_b32_e32 v8, v0
	v_mov_b32_e32 v9, v0
	v_mov_b32_e32 v10, v0
	v_mov_b32_e32 v11, v0
	v_mov_b32_e32 v12, v0
	v_mov_b32_e32 v13, v0
	v_mov_b64_e32 v[30:31], v[14:15]
	v_mov_b64_e32 v[46:47], v[14:15]
	v_mov_b64_e32 v[62:63], v[14:15]
	v_mov_b64_e32 v[78:79], v[14:15]
	v_mov_b32_e32 v155, s27
	s_mov_b32 s26, 0
	v_mov_b32_e32 v143, 0
	v_mov_b32_e32 v185, 0xff800000
	s_mov_b32 s27, 63
	s_or_b32 s29, s11, 1
	v_mov_b64_e32 v[28:29], v[12:13]
	v_mov_b64_e32 v[26:27], v[10:11]
	v_mov_b64_e32 v[24:25], v[8:9]
	v_mov_b64_e32 v[22:23], v[6:7]
	v_mov_b64_e32 v[20:21], v[4:5]
	v_mov_b64_e32 v[18:19], v[2:3]
	v_mov_b64_e32 v[16:17], v[0:1]
	s_or_b32 s49, s10, 31
	v_mov_b64_e32 v[44:45], v[12:13]
	v_mov_b64_e32 v[42:43], v[10:11]
	v_mov_b64_e32 v[40:41], v[8:9]
	v_mov_b64_e32 v[38:39], v[6:7]
	v_mov_b64_e32 v[36:37], v[4:5]
	v_mov_b64_e32 v[34:35], v[2:3]
	v_mov_b64_e32 v[32:33], v[0:1]
	v_mov_b64_e32 v[60:61], v[12:13]
	v_mov_b64_e32 v[58:59], v[10:11]
	v_mov_b64_e32 v[56:57], v[8:9]
	v_mov_b64_e32 v[54:55], v[6:7]
	v_mov_b64_e32 v[52:53], v[4:5]
	v_mov_b64_e32 v[50:51], v[2:3]
	v_mov_b64_e32 v[48:49], v[0:1]
	s_mov_b32 s30, 0
	v_mov_b64_e32 v[76:77], v[12:13]
	v_mov_b64_e32 v[74:75], v[10:11]
	v_mov_b64_e32 v[72:73], v[8:9]
	v_mov_b64_e32 v[70:71], v[6:7]
	v_mov_b64_e32 v[68:69], v[4:5]
	v_mov_b64_e32 v[66:67], v[2:3]
	v_mov_b64_e32 v[64:65], v[0:1]
	s_waitcnt vmcnt(0)
	s_waitcnt vmcnt(4) lgkmcnt(0)
	s_barrier
	s_mov_b32 s60, 0
	s_mov_b32 s61, 0
	s_mov_b32 s62, m0
	v_mov_b32_e32 v240, 0
	v_mov_b32_e32 v241, 0
	v_mov_b32_e32 v242, 0
	v_mov_b32_e32 v243, 0
	v_mov_b32_e32 v244, 0
	v_mov_b32_e32 v245, 0
	v_mov_b32_e32 v246, 0
	v_mov_b32_e32 v247, 0
	v_mov_b32_e32 v248, 0
	v_mov_b32_e32 v249, 0
	v_mov_b32_e32 v250, 0
	v_mov_b32_e32 v251, 0
	v_mov_b32_e32 v252, 0
	v_mov_b32_e32 v253, 0
	v_mov_b32_e32 v254, 0
	v_mov_b32_e32 v255, 0
	s_add_i32 s66, s30, 2
	s_cmp_lt_u32 s30, s11
	s_cselect_b32 s64, s66, s29
	s_lshl_b32 s65, s64, 6
	s_mul_i32 s64, s64, 0x60000
	s_mul_hi_u32 s65, s65, 0x1800
	s_add_u32 s64, s24, s64
	s_addc_u32 s65, s25, s65
	s_lshl_b32 s66, s66, 15
	s_and_b32 s66, s66, 0x18000
	s_add_i32 s67, s66, s22
	s_add_i32 s68, s66, s28
	s_add_i32 s69, s66, s36
	s_add_i32 s70, s66, s37
	s_and_b64 vcc, exec, s[20:21]
	s_cbranch_vccnz .Ldf2a_loop

; DI f32x16 mfma32(bf16x8 a, bf16x8 b, f32x16 c) { return __builtin_amdgcn_mfma_f32_32x32x16_bf16(a, b, c, 0, 0, 0); }
; #define DF_VLD(VF, VOFF, H) do { _Pragma("unroll") for (int d2 = 0; d2 < 2; ++d2) { LAS unsigned char* vb_ = lds3 + (VOFF) + (2 * (H) + d2) * 4096; VF[2 * d2] = vfrag(vb_); VF[2 * d2 + 1] = vfrag(vb_ + 1024); } } while (0)
; #define DF_PVM(VF, P0, P1, H) do { _Pragma("unroll") for (int d2 = 0; d2 < 2; ++d2) { o[2 * (H) + d2] = mfma32(VF[2 * d2], P0, o[2 * (H) + d2]); o[2 * (H) + d2] = mfma32(VF[2 * d2 + 1], P1, o[2 * (H) + d2]); } } while (0)
; DI void diff_stage(const unsigned char* lds, LAS unsigned char* lds3, int buf, int t, int comp, int q0, int r32, int hi, int vlane, bool skew,
;                    const bf16x8 (&qf)[4], f32x16 (&o)[4], float& m, float& l, bf16x8 (&pp)[4], int& pvo, bool& have_prev) {
;     ...
;     if (skew && have_prev) {
; #pragma unroll
;         for (int sub = 0; sub < 2; ++sub) { DF_VLD(vf, pvo + sub * 2048, 0); DF_PVM(vf, pp[2 * sub], pp[2 * sub + 1], 0); DF_VLD(vf, pvo + sub * 2048, 1); DF_PVM(vf, pp[2 * sub], pp[2 * sub + 1], 1); }
;     }
;     f32x16 s0, s1;
; #pragma unroll
;     for (int i = 0; i < 16; ++i) { s0[i] = 0.f; s1[i] = 0.f; }
;     {
;         bf16x8 k0f[4], k1f[4];
; #pragma unroll
;         for (int c = 0; c < 4; ++c) { k0f[c] = *(const bf16x8*)(sb + ((32 * c) ^ ke16)); k1f[c] = *(const bf16x8*)(sb + 32 * 128 + ((32 * c) ^ ke16)); }
; #pragma unroll
;         for (int c = 0; c < 4; ++c) { s0 = mfma32(k0f[c], qf[c], s0); s1 = mfma32(k1f[c], qf[c], s1); }
;     }
;     if (k0 + 63 > q0) {
;         const int dq = q0 + r32 - k0 - 4 * hi;
; #pragma unroll
;         for (int i = 0; i < 16; ++i) { const int ci = (i & 3) + 8 * (i >> 2); s0[i] = (ci > dq) ? -INFINITY : s0[i]; s1[i] = (ci + 32 > dq) ? -INFINITY : s1[i]; }
;     }
.Ldf2bs_noresc:
	s_waitcnt lgkmcnt(7)
	v_mfma_f32_32x32x16_bf16 v[96:111], v[208:211], v[124:127], 0
	s_waitcnt lgkmcnt(6)
	v_mfma_f32_32x32x16_bf16 v[80:95], v[212:215], v[124:127], 0
	s_waitcnt lgkmcnt(5)
	v_mfma_f32_32x32x16_bf16 v[96:111], v[216:219], v[120:123], v[96:111]
	s_waitcnt lgkmcnt(4)
	v_mfma_f32_32x32x16_bf16 v[80:95], v[220:223], v[120:123], v[80:95]
	s_waitcnt lgkmcnt(3)
	v_mfma_f32_32x32x16_bf16 v[96:111], v[224:227], v[116:119], v[96:111]
	s_waitcnt lgkmcnt(2)
	v_mfma_f32_32x32x16_bf16 v[80:95], v[228:231], v[116:119], v[80:95]
	s_waitcnt lgkmcnt(1)
	v_mfma_f32_32x32x16_bf16 v[96:111], v[232:235], v[112:115], v[96:111]
	s_waitcnt lgkmcnt(0)
	v_mfma_f32_32x32x16_bf16 v[80:95], v[236:239], v[112:115], v[80:95]
	ds_read_b64_tr_b16 v[208:209], v6 offset:16384
	ds_read_b64_tr_b16 v[210:211], v6 offset:16896
	ds_read_b64_tr_b16 v[212:213], v6 offset:17408
	ds_read_b64_tr_b16 v[214:215], v6 offset:17920
	ds_read_b64_tr_b16 v[216:217], v6 offset:20480
	ds_read_b64_tr_b16 v[218:219], v6 offset:20992
	ds_read_b64_tr_b16 v[220:221], v6 offset:21504
	ds_read_b64_tr_b16 v[222:223], v6 offset:22016
	ds_read_b64_tr_b16 v[224:225], v6 offset:24576
	ds_read_b64_tr_b16 v[226:227], v6 offset:25088
	ds_read_b64_tr_b16 v[228:229], v6 offset:25600
	ds_read_b64_tr_b16 v[230:231], v6 offset:26112
	s_waitcnt lgkmcnt(10)
	v_mfma_f32_32x32x16_bf16 v[64:79], v[208:211], v[240:243], v[64:79]
	ds_read_b64_tr_b16 v[232:233], v6 offset:28672
	ds_read_b64_tr_b16 v[234:235], v6 offset:29184
	s_waitcnt lgkmcnt(10)
	v_mfma_f32_32x32x16_bf16 v[64:79], v[212:215], v[244:247], v[64:79]
	ds_read_b64_tr_b16 v[236:237], v6 offset:29696
	ds_read_b64_tr_b16 v[238:239], v6 offset:30208
	s_waitcnt lgkmcnt(10)
	v_mfma_f32_32x32x16_bf16 v[48:63], v[216:219], v[240:243], v[48:63]
	ds_read_b64_tr_b16 v[208:209], v6 offset:18432
	ds_read_b64_tr_b16 v[210:211], v6 offset:18944
	s_waitcnt lgkmcnt(10)
	v_mfma_f32_32x32x16_bf16 v[48:63], v[220:223], v[244:247], v[48:63]
	ds_read_b64_tr_b16 v[212:213], v6 offset:19456
	ds_read_b64_tr_b16 v[214:215], v6 offset:19968
	s_waitcnt lgkmcnt(10)
	v_mfma_f32_32x32x16_bf16 v[32:47], v[224:227], v[240:243], v[32:47]
	ds_read_b64_tr_b16 v[216:217], v6 offset:22528
	ds_read_b64_tr_b16 v[218:219], v6 offset:23040
	s_waitcnt lgkmcnt(10)
	v_mfma_f32_32x32x16_bf16 v[32:47], v[228:231], v[244:247], v[32:47]
	ds_read_b64_tr_b16 v[220:221], v6 offset:23552
	ds_read_b64_tr_b16 v[222:223], v6 offset:24064
	s_waitcnt lgkmcnt(10)
	v_mfma_f32_32x32x16_bf16 v[16:31], v[232:235], v[240:243], v[16:31]
	ds_read_b64_tr_b16 v[224:225], v6 offset:26624
	ds_read_b64_tr_b16 v[226:227], v6 offset:27136
	s_waitcnt lgkmcnt(10)
	v_mfma_f32_32x32x16_bf16 v[16:31], v[236:239], v[244:247], v[16:31]
	ds_read_b64_tr_b16 v[228:229], v6 offset:27648
	ds_read_b64_tr_b16 v[230:231], v6 offset:28160
	s_waitcnt lgkmcnt(10)
	v_mfma_f32_32x32x16_bf16 v[64:79], v[208:211], v[248:251], v[64:79]
	ds_read_b64_tr_b16 v[232:233], v6 offset:30720
	ds_read_b64_tr_b16 v[234:235], v6 offset:31232
	s_waitcnt lgkmcnt(10)
	v_mfma_f32_32x32x16_bf16 v[64:79], v[212:215], v[252:255], v[64:79]
	ds_read_b64_tr_b16 v[236:237], v6 offset:31744
	ds_read_b64_tr_b16 v[238:239], v6 offset:32256
	s_waitcnt lgkmcnt(10)
	v_mfma_f32_32x32x16_bf16 v[48:63], v[216:219], v[248:251], v[48:63]
	s_waitcnt lgkmcnt(8)
	v_mfma_f32_32x32x16_bf16 v[48:63], v[220:223], v[252:255], v[48:63]
	s_waitcnt lgkmcnt(6)
	v_mfma_f32_32x32x16_bf16 v[32:47], v[224:227], v[248:251], v[32:47]
	s_waitcnt lgkmcnt(4)
	v_mfma_f32_32x32x16_bf16 v[32:47], v[228:231], v[252:255], v[32:47]
	s_waitcnt lgkmcnt(2)
	v_mfma_f32_32x32x16_bf16 v[16:31], v[232:235], v[248:251], v[16:31]
	s_waitcnt lgkmcnt(0)
	v_mfma_f32_32x32x16_bf16 v[16:31], v[236:239], v[252:255], v[16:31]
	s_cmp_le_u32 s27, s10
	s_cbranch_scc1 .Ldf2b_nodiag
	s_nop 7
	v_cmp_lt_i32_e32 vcc, -1, v183
	s_nop 1
	v_cndmask_b32_e32 v96, v176, v96, vcc
	v_cmp_lt_i32_e32 vcc, 31, v183
	s_nop 1
	v_cndmask_b32_e32 v80, v176, v80, vcc
	v_cmp_lt_i32_e32 vcc, 0, v183
	s_nop 1
	v_cndmask_b32_e32 v97, v176, v97, vcc
	v_cmp_lt_i32_e32 vcc, 32, v183
	s_nop 1
	v_cndmask_b32_e32 v81, v176, v81, vcc
	v_cmp_lt_i32_e32 vcc, 1, v183
	s_nop 1
	v_cndmask_b32_e32 v98, v176, v98, vcc
	v_cmp_lt_i32_e32 vcc, 33, v183
	s_nop 1
	v_cndmask_b32_e32 v82, v176, v82, vcc
	v_cmp_lt_i32_e32 vcc, 2, v183
	s_nop 1
	v_cndmask_b32_e32 v99, v176, v99, vcc
	v_cmp_lt_i32_e32 vcc, 34, v183
	s_nop 1
	v_cndmask_b32_e32 v83, v176, v83, vcc
	v_cmp_lt_i32_e32 vcc, 7, v183
	s_nop 1
	v_cndmask_b32_e32 v100, v176, v100, vcc
	v_cmp_lt_i32_e32 vcc, 39, v183
	s_nop 1
	v_cndmask_b32_e32 v84, v176, v84, vcc
	v_cmp_lt_i32_e32 vcc, 8, v183
	s_nop 1
	v_cndmask_b32_e32 v101, v176, v101, vcc
	v_cmp_lt_i32_e32 vcc, 40, v183
	s_nop 1
	v_cndmask_b32_e32 v85, v176, v85, vcc
	v_cmp_lt_i32_e32 vcc, 9, v183
	s_nop 1
	v_cndmask_b32_e32 v102, v176, v102, vcc
	v_cmp_lt_i32_e32 vcc, 41, v183
	s_nop 1
	v_cndmask_b32_e32 v86, v176, v86, vcc
	v_cmp_lt_i32_e32 vcc, 10, v183
	s_nop 1
	v_cndmask_b32_e32 v103, v176, v103, vcc
	v_cmp_lt_i32_e32 vcc, 42, v183
	s_nop 1
	v_cndmask_b32_e32 v87, v176, v87, vcc
	v_cmp_lt_i32_e32 vcc, 15, v183
	s_nop 1
	v_cndmask_b32_e32 v104, v176, v104, vcc
	v_cmp_lt_i32_e32 vcc, 47, v183
	s_nop 1
	v_cndmask_b32_e32 v88, v176, v88, vcc
	v_cmp_lt_i32_e32 vcc, 16, v183
	s_nop 1
	v_cndmask_b32_e32 v105, v176, v105, vcc
	v_cmp_lt_i32_e32 vcc, 48, v183
	s_nop 1
	v_cndmask_b32_e32 v89, v176, v89, vcc
	v_cmp_lt_i32_e32 vcc, 17, v183
	s_nop 1
	v_cndmask_b32_e32 v106, v176, v106, vcc
	v_cmp_lt_i32_e32 vcc, 49, v183
	s_nop 1
	v_cndmask_b32_e32 v90, v176, v90, vcc
	v_cmp_lt_i32_e32 vcc, 18, v183
	s_nop 1
	v_cndmask_b32_e32 v107, v176, v107, vcc
	v_cmp_lt_i32_e32 vcc, 50, v183
	s_nop 1
	v_cndmask_b32_e32 v91, v176, v91, vcc
	v_cmp_lt_i32_e32 vcc, 23, v183
	s_nop 1
	v_cndmask_b32_e32 v108, v176, v108, vcc
	v_cmp_lt_i32_e32 vcc, 55, v183
	s_nop 1
	v_cndmask_b32_e32 v92, v176, v92, vcc
	v_cmp_lt_i32_e32 vcc, 24, v183
	s_nop 1
	v_cndmask_b32_e32 v109, v176, v109, vcc
	v_cmp_lt_i32_e32 vcc, 56, v183
	s_nop 1
	v_cndmask_b32_e32 v93, v176, v93, vcc
	v_cmp_lt_i32_e32 vcc, 25, v183
	s_nop 1
	v_cndmask_b32_e32 v110, v176, v110, vcc
	v_cmp_lt_i32_e32 vcc, 57, v183
	s_nop 1
	v_cndmask_b32_e32 v94, v176, v94, vcc
	v_cmp_lt_i32_e32 vcc, 26, v183
	s_nop 1
	v_cndmask_b32_e32 v111, v176, v111, vcc
	v_cmp_lt_i32_e32 vcc, 58, v183
	s_nop 1
	v_cndmask_b32_e32 v95, v176, v95, vcc
; DI float xhalf(float v) { return __shfl_xor(v, 32); }
; DI float fexp2(float x) { return __builtin_amdgcn_exp2f(x); }
; #define DF_VLD(VF, VOFF, H) do { _Pragma("unroll") for (int d2 = 0; d2 < 2; ++d2) { LAS unsigned char* vb_ = lds3 + (VOFF) + (2 * (H) + d2) * 4096; VF[2 * d2] = vfrag(vb_); VF[2 * d2 + 1] = vfrag(vb_ + 1024); } } while (0)
; #define DF_PVM(VF, P0, P1, H) do { _Pragma("unroll") for (int d2 = 0; d2 < 2; ++d2) { o[2 * (H) + d2] = mfma32(VF[2 * d2], P0, o[2 * (H) + d2]); o[2 * (H) + d2] = mfma32(VF[2 * d2 + 1], P1, o[2 * (H) + d2]); } } while (0)
; DI void diff_stage(const unsigned char* lds, LAS unsigned char* lds3, int buf, int t, int comp, int q0, int r32, int hi, int vlane, bool skew,
;                    const bf16x8 (&qf)[4], f32x16 (&o)[4], float& m, float& l, bf16x8 (&pp)[4], int& pvo, bool& have_prev) {
;     ...
;     float mx = fmaxf(fmaxf(s0[0], s0[1]), s1[0]);
; #pragma unroll
;     for (int i = 1; i < 15; i += 2) { mx = fmaxf(fmaxf(mx, s0[i + 1]), s0[i + 2 > 15 ? 15 : i + 2]); mx = fmaxf(fmaxf(mx, s1[i]), s1[i + 1]); }
;     mx = fmaxf(mx, s1[15]);
;     mx = fmaxf(mx, xhalf(mx)) * SCL2;
;     if (__any(mx > m + 8.f)) {
;         const float mn = fmaxf(m, mx), al = fexp2(m - mn); l *= al; m = mn;
; #pragma unroll
;         for (int dt = 0; dt < 4; ++dt)
; #pragma unroll
;             for (int i = 0; i < 16; ++i) o[dt][i] *= al;
;     }
;     float sum0 = 0.f, sum1 = 0.f;
; #pragma unroll
;     for (int i = 0; i < 16; ++i) { s0[i] = fexp2(__builtin_fmaf(s0[i], SCL2, -m)); sum0 += s0[i]; s1[i] = fexp2(__builtin_fmaf(s1[i], SCL2, -m)); sum1 += s1[i]; }
;     l += sum0 + sum1;
;     const int vo = buf * DF_STAGE + DF_V + vlane;
;     if (!skew) {
;         const bf16x8 p00 = packP<0>(s0), p01 = packP<1>(s0);
;         DF_VLD(vf, vo, 0); DF_PVM(vf, p00, p01, 0); DF_VLD(vf, vo, 1); DF_PVM(vf, p00, p01, 1);
;         const bf16x8 p10 = packP<0>(s1), p11 = packP<1>(s1);
;         DF_VLD(vf, vo + 2048, 0); DF_PVM(vf, p10, p11, 0); DF_VLD(vf, vo + 2048, 1); DF_PVM(vf, p10, p11, 1);
;     } else { pp[0] = packP<0>(s0); pp[1] = packP<1>(s0); pp[2] = packP<0>(s1); pp[3] = packP<1>(s1); pvo = vo; have_prev = true; }
.Ldf2b_nodiag:
	v_max3_f32 v1, v96, v97, v98
	v_max3_f32 v1, v1, v99, v100
	v_max3_f32 v1, v1, v101, v102
	v_max3_f32 v1, v1, v103, v104
	v_max3_f32 v1, v1, v105, v106
	v_max3_f32 v1, v1, v107, v108
	v_max3_f32 v1, v1, v109, v110
	v_max3_f32 v1, v1, v111, v80
	v_max3_f32 v1, v1, v81, v82
	v_max3_f32 v1, v1, v83, v84
	v_max3_f32 v1, v1, v85, v86
	v_max3_f32 v1, v1, v87, v88
	v_max3_f32 v1, v1, v89, v90
	v_max3_f32 v1, v1, v91, v92
	v_max3_f32 v1, v1, v93, v94
	v_max_f32_e32 v1, v1, v95
	v_mov_b32_e32 v14, v1
	s_nop 1
	v_permlane32_swap_b32_e32 v1, v14
	v_add_f32_e32 v15, 0x41000000, v185
	v_max_f32_e32 v1, v1, v14
	v_mul_f32_e32 v1, 0x3e38aa3b, v1
	v_cmp_gt_f32_e32 vcc, v1, v15
	s_cbranch_vccz .Ldf2b_notrig
	v_max_f32_e32 v1, v1, v1
	v_max_f32_e32 v14, v185, v185
	v_max_f32_e32 v1, v14, v1
	v_sub_f32_e32 v14, v185, v1
	v_exp_f32_e32 v206, v14
	v_mov_b32_e32 v185, v1
	s_mov_b32 s60, 1
	v_mul_f32_e32 v143, v143, v206
.Ldf2b_notrig:
	v_fma_f32 v96, v96, s44, -v185
	v_fma_f32 v97, v97, s44, -v185
	v_exp_f32_e32 v96, v96
	v_exp_f32_e32 v97, v97
	v_fma_f32 v98, v98, s44, -v185
	v_fma_f32 v99, v99, s44, -v185
	v_exp_f32_e32 v98, v98
	v_exp_f32_e32 v99, v99
	v_fma_f32 v100, v100, s44, -v185
	v_fma_f32 v101, v101, s44, -v185
	v_exp_f32_e32 v100, v100
	v_exp_f32_e32 v101, v101
	v_fma_f32 v102, v102, s44, -v185
	v_fma_f32 v103, v103, s44, -v185
	v_exp_f32_e32 v102, v102
	v_exp_f32_e32 v103, v103
	v_fma_f32 v104, v104, s44, -v185
	v_fma_f32 v105, v105, s44, -v185
	v_exp_f32_e32 v104, v104
	v_exp_f32_e32 v105, v105
	v_fma_f32 v106, v106, s44, -v185
	v_fma_f32 v107, v107, s44, -v185
	v_exp_f32_e32 v106, v106
	v_exp_f32_e32 v107, v107
	v_fma_f32 v108, v108, s44, -v185
	v_fma_f32 v109, v109, s44, -v185
	v_exp_f32_e32 v108, v108
	v_exp_f32_e32 v109, v109
	v_fma_f32 v110, v110, s44, -v185
	v_fma_f32 v111, v111, s44, -v185
	v_exp_f32_e32 v110, v110
	v_exp_f32_e32 v111, v111
	v_add_f32_e32 v14, v96, v97
	v_add_f32_e32 v14, v14, v98
	v_add_f32_e32 v14, v14, v99
	v_add_f32_e32 v14, v14, v100
	v_add_f32_e32 v14, v14, v101
	v_add_f32_e32 v14, v14, v102
	v_add_f32_e32 v14, v14, v103
	v_add_f32_e32 v14, v14, v104
	v_add_f32_e32 v14, v14, v105
	v_add_f32_e32 v14, v14, v106
	v_add_f32_e32 v14, v14, v107
	v_add_f32_e32 v14, v14, v108
	v_add_f32_e32 v14, v14, v109
	v_add_f32_e32 v14, v14, v110
	v_add_f32_e32 v14, v14, v111
	v_fma_f32 v80, v80, s44, -v185
	v_fma_f32 v81, v81, s44, -v185
	v_exp_f32_e32 v80, v80
	v_exp_f32_e32 v81, v81
	v_fma_f32 v82, v82, s44, -v185
	v_fma_f32 v83, v83, s44, -v185
	v_exp_f32_e32 v82, v82
	v_exp_f32_e32 v83, v83
	v_fma_f32 v84, v84, s44, -v185
	v_fma_f32 v85, v85, s44, -v185
	v_exp_f32_e32 v84, v84
	v_exp_f32_e32 v85, v85
	v_fma_f32 v86, v86, s44, -v185
	v_fma_f32 v87, v87, s44, -v185
	v_exp_f32_e32 v86, v86
	v_exp_f32_e32 v87, v87
	v_fma_f32 v88, v88, s44, -v185
	v_fma_f32 v89, v89, s44, -v185
	v_exp_f32_e32 v88, v88
	v_exp_f32_e32 v89, v89
	v_fma_f32 v90, v90, s44, -v185
	v_fma_f32 v91, v91, s44, -v185
	v_exp_f32_e32 v90, v90
	v_exp_f32_e32 v91, v91
	v_fma_f32 v92, v92, s44, -v185
	v_fma_f32 v93, v93, s44, -v185
	v_exp_f32_e32 v92, v92
	v_exp_f32_e32 v93, v93
	v_fma_f32 v94, v94, s44, -v185
	v_fma_f32 v95, v95, s44, -v185
	v_exp_f32_e32 v94, v94
	v_exp_f32_e32 v95, v95
	v_add_f32_e32 v15, v80, v81
	v_add_f32_e32 v15, v15, v82
	v_add_f32_e32 v15, v15, v83
	v_add_f32_e32 v15, v15, v84
	v_add_f32_e32 v15, v15, v85
	v_add_f32_e32 v15, v15, v86
	v_add_f32_e32 v15, v15, v87
	v_add_f32_e32 v15, v15, v88
	v_add_f32_e32 v15, v15, v89
	v_add_f32_e32 v15, v15, v90
	v_add_f32_e32 v15, v15, v91
	v_add_f32_e32 v15, v15, v92
	v_add_f32_e32 v15, v15, v93
	v_add_f32_e32 v15, v15, v94
	v_add_f32_e32 v15, v15, v95
	v_add_f32_e32 v14, v14, v15
	v_add_f32_e32 v143, v143, v14
	v_cvt_pk_bf16_f32 v240, v96, v97
	v_cvt_pk_bf16_f32 v241, v98, v99
	v_cvt_pk_bf16_f32 v242, v100, v101
	v_cvt_pk_bf16_f32 v243, v102, v103
	v_cvt_pk_bf16_f32 v244, v104, v105
	v_cvt_pk_bf16_f32 v245, v106, v107
	v_cvt_pk_bf16_f32 v246, v108, v109
	v_cvt_pk_bf16_f32 v247, v110, v111
	v_cvt_pk_bf16_f32 v248, v80, v81
	v_cvt_pk_bf16_f32 v249, v82, v83
	v_cvt_pk_bf16_f32 v250, v84, v85
	v_cvt_pk_bf16_f32 v251, v86, v87
	v_cvt_pk_bf16_f32 v252, v88, v89
	v_cvt_pk_bf16_f32 v253, v90, v91
	v_cvt_pk_bf16_f32 v254, v92, v93
	v_cvt_pk_bf16_f32 v255, v94, v95
	s_mov_b32 s61, 1
	s_branch .Ldf2b_bar

; DI f32x16 mfma32(bf16x8 a, bf16x8 b, f32x16 c) { return __builtin_amdgcn_mfma_f32_32x32x16_bf16(a, b, c, 0, 0, 0); }
; #define DF_VLD(VF, VOFF, H) do { _Pragma("unroll") for (int d2 = 0; d2 < 2; ++d2) { LAS unsigned char* vb_ = lds3 + (VOFF) + (2 * (H) + d2) * 4096; VF[2 * d2] = vfrag(vb_); VF[2 * d2 + 1] = vfrag(vb_ + 1024); } } while (0)
; DI void diff_stage(const unsigned char* lds, LAS unsigned char* lds3, int buf, int t, int comp, int q0, int r32, int hi, int vlane, bool skew,
;                    const bf16x8 (&qf)[4], f32x16 (&o)[4], float& m, float& l, bf16x8 (&pp)[4], int& pvo, bool& have_prev) {
;     const int k0 = 64 * t;
;     if (k0 > q0 + 31) return;
;     const unsigned char* sb = lds + buf * DF_STAGE + comp * DF_K2 + r32 * 128; const int ke16 = (hi ^ ((r32 >> 1) & 7)) * 16;
;     bf16x8 vf[4];
;     if (skew && have_prev) {
; #pragma unroll
;         for (int sub = 0; sub < 2; ++sub) { DF_VLD(vf, pvo + sub * 2048, 0); DF_PVM(vf, pp[2 * sub], pp[2 * sub + 1], 0); DF_VLD(vf, pvo + sub * 2048, 1); DF_PVM(vf, pp[2 * sub], pp[2 * sub + 1], 1); }
;     }
;     f32x16 s0, s1;
; #pragma unroll
;     for (int i = 0; i < 16; ++i) { s0[i] = 0.f; s1[i] = 0.f; }
;     {
;         bf16x8 k0f[4], k1f[4];
; #pragma unroll
;         for (int c = 0; c < 4; ++c) { k0f[c] = *(const bf16x8*)(sb + ((32 * c) ^ ke16)); k1f[c] = *(const bf16x8*)(sb + 32 * 128 + ((32 * c) ^ ke16)); }
; #pragma unroll
;         for (int c = 0; c < 4; ++c) { s0 = mfma32(k0f[c], qf[c], s0); s1 = mfma32(k1f[c], qf[c], s1); }
;     }
;     if (k0 + 63 > q0) {
;         const int dq = q0 + r32 - k0 - 4 * hi;
; #pragma unroll
;         for (int i = 0; i < 16; ++i) { const int ci = (i & 3) + 8 * (i >> 2); s0[i] = (ci > dq) ? -INFINITY : s0[i]; s1[i] = (ci + 32 > dq) ? -INFINITY : s1[i]; }
;     }
; DI void diff_unit(const Args& A, const bf16_t* QKV, bf16_t* ATT, unsigned char* lds, LAS unsigned char* lds3, int b, int head, int qb, int tid, int wid, int lane) {
;     ...
;     for (int t = 0; t < nst; ++t) {
;         { const int tl = (t + 2 < nst) ? t + 2 : nst - 1; DF_DMA(tl, (t + 2) & 3); }
;         diff_stage(lds, lds3, t & 3, t, comp, q0, r32, hi, vlane, skew, qf, o, m, l, pp, pvo, have_prev);
.Ldf2a_loop:
	s_sub_i32 s71, s27, 63
	s_cmp_gt_u32 s71, s49
	s_cbranch_scc1 .Ldf2a_skip
	s_and_b32 s31, s26, 0x18000
	v_add_u32_e32 v2, s31, v160
	v_add_u32_e32 v3, v2, v161
	v_add_u32_e32 v4, v2, v162
	v_add_u32_e32 v5, v2, v163
	v_add_u32_e32 v2, v2, v164
	ds_read_b128 v[208:211], v3
	ds_read_b128 v[212:215], v3 offset:4096
	ds_read_b128 v[216:219], v4
	ds_read_b128 v[220:223], v4 offset:4096
	ds_read_b128 v[224:227], v5
	ds_read_b128 v[228:231], v5 offset:4096
	ds_read_b128 v[232:235], v2
	ds_read_b128 v[236:239], v2 offset:4096
	s_mov_b32 m0, s67
	s_nop 0
	global_load_lds_dwordx4 v156, s[64:65]
	s_mov_b32 m0, s68
	s_nop 0
	global_load_lds_dwordx4 v159, s[64:65]
	s_mov_b32 m0, s69
	s_nop 0
	global_load_lds_dwordx4 v157, s[64:65]
	s_mov_b32 m0, s70
	s_nop 0
	global_load_lds_dwordx4 v158, s[64:65]
	v_add_u32_e32 v6, s31, v165
	s_waitcnt lgkmcnt(7)
	v_mfma_f32_32x32x16_bf16 v[96:111], v[208:211], v[124:127], 0
	s_waitcnt lgkmcnt(6)
	v_mfma_f32_32x32x16_bf16 v[80:95], v[212:215], v[124:127], 0
	s_waitcnt lgkmcnt(5)
	v_mfma_f32_32x32x16_bf16 v[96:111], v[216:219], v[120:123], v[96:111]
	s_waitcnt lgkmcnt(4)
	v_mfma_f32_32x32x16_bf16 v[80:95], v[220:223], v[120:123], v[80:95]
	s_waitcnt lgkmcnt(3)
	v_mfma_f32_32x32x16_bf16 v[96:111], v[224:227], v[116:119], v[96:111]
	s_waitcnt lgkmcnt(2)
	v_mfma_f32_32x32x16_bf16 v[80:95], v[228:231], v[116:119], v[80:95]
	s_waitcnt lgkmcnt(1)
	v_mfma_f32_32x32x16_bf16 v[96:111], v[232:235], v[112:115], v[96:111]
	s_waitcnt lgkmcnt(0)
	v_mfma_f32_32x32x16_bf16 v[80:95], v[236:239], v[112:115], v[80:95]
	ds_read_b64_tr_b16 v[208:209], v6 offset:16384
	ds_read_b64_tr_b16 v[210:211], v6 offset:16896
	ds_read_b64_tr_b16 v[212:213], v6 offset:17408
	ds_read_b64_tr_b16 v[214:215], v6 offset:17920
	ds_read_b64_tr_b16 v[216:217], v6 offset:20480
	ds_read_b64_tr_b16 v[218:219], v6 offset:20992
	ds_read_b64_tr_b16 v[220:221], v6 offset:21504
	ds_read_b64_tr_b16 v[222:223], v6 offset:22016
	ds_read_b64_tr_b16 v[224:225], v6 offset:24576
	ds_read_b64_tr_b16 v[226:227], v6 offset:25088
	ds_read_b64_tr_b16 v[228:229], v6 offset:25600
	ds_read_b64_tr_b16 v[230:231], v6 offset:26112
	s_cmp_le_u32 s27, s10
	s_cbranch_scc1 .Ldf2a_nodiag
	s_nop 7
	v_cmp_lt_i32_e32 vcc, -1, v183
	s_nop 1
	v_cndmask_b32_e32 v96, v176, v96, vcc
	v_cmp_lt_i32_e32 vcc, 31, v183
	s_nop 1
	v_cndmask_b32_e32 v80, v176, v80, vcc
	v_cmp_lt_i32_e32 vcc, 0, v183
	s_nop 1
	v_cndmask_b32_e32 v97, v176, v97, vcc
	v_cmp_lt_i32_e32 vcc, 32, v183
	s_nop 1
	v_cndmask_b32_e32 v81, v176, v81, vcc
	v_cmp_lt_i32_e32 vcc, 1, v183
	s_nop 1
	v_cndmask_b32_e32 v98, v176, v98, vcc
	v_cmp_lt_i32_e32 vcc, 33, v183
	s_nop 1
	v_cndmask_b32_e32 v82, v176, v82, vcc
	v_cmp_lt_i32_e32 vcc, 2, v183
	s_nop 1
	v_cndmask_b32_e32 v99, v176, v99, vcc
	v_cmp_lt_i32_e32 vcc, 34, v183
	s_nop 1
	v_cndmask_b32_e32 v83, v176, v83, vcc
	v_cmp_lt_i32_e32 vcc, 7, v183
	s_nop 1
	v_cndmask_b32_e32 v100, v176, v100, vcc
	v_cmp_lt_i32_e32 vcc, 39, v183
	s_nop 1
	v_cndmask_b32_e32 v84, v176, v84, vcc
	v_cmp_lt_i32_e32 vcc, 8, v183
	s_nop 1
	v_cndmask_b32_e32 v101, v176, v101, vcc
	v_cmp_lt_i32_e32 vcc, 40, v183
	s_nop 1
	v_cndmask_b32_e32 v85, v176, v85, vcc
	v_cmp_lt_i32_e32 vcc, 9, v183
	s_nop 1
	v_cndmask_b32_e32 v102, v176, v102, vcc
	v_cmp_lt_i32_e32 vcc, 41, v183
	s_nop 1
	v_cndmask_b32_e32 v86, v176, v86, vcc
	v_cmp_lt_i32_e32 vcc, 10, v183
	s_nop 1
	v_cndmask_b32_e32 v103, v176, v103, vcc
	v_cmp_lt_i32_e32 vcc, 42, v183
	s_nop 1
	v_cndmask_b32_e32 v87, v176, v87, vcc
	v_cmp_lt_i32_e32 vcc, 15, v183
	s_nop 1
	v_cndmask_b32_e32 v104, v176, v104, vcc
	v_cmp_lt_i32_e32 vcc, 47, v183
	s_nop 1
	v_cndmask_b32_e32 v88, v176, v88, vcc
	v_cmp_lt_i32_e32 vcc, 16, v183
	s_nop 1
	v_cndmask_b32_e32 v105, v176, v105, vcc
	v_cmp_lt_i32_e32 vcc, 48, v183
	s_nop 1
	v_cndmask_b32_e32 v89, v176, v89, vcc
	v_cmp_lt_i32_e32 vcc, 17, v183
	s_nop 1
	v_cndmask_b32_e32 v106, v176, v106, vcc
	v_cmp_lt_i32_e32 vcc, 49, v183
	s_nop 1
	v_cndmask_b32_e32 v90, v176, v90, vcc
	v_cmp_lt_i32_e32 vcc, 18, v183
	s_nop 1
	v_cndmask_b32_e32 v107, v176, v107, vcc
	v_cmp_lt_i32_e32 vcc, 50, v183
	s_nop 1
	v_cndmask_b32_e32 v91, v176, v91, vcc
	v_cmp_lt_i32_e32 vcc, 23, v183
	s_nop 1
	v_cndmask_b32_e32 v108, v176, v108, vcc
	v_cmp_lt_i32_e32 vcc, 55, v183
	s_nop 1
	v_cndmask_b32_e32 v92, v176, v92, vcc
	v_cmp_lt_i32_e32 vcc, 24, v183
	s_nop 1
	v_cndmask_b32_e32 v109, v176, v109, vcc
	v_cmp_lt_i32_e32 vcc, 56, v183
	s_nop 1
	v_cndmask_b32_e32 v93, v176, v93, vcc
	v_cmp_lt_i32_e32 vcc, 25, v183
	s_nop 1
	v_cndmask_b32_e32 v110, v176, v110, vcc
	v_cmp_lt_i32_e32 vcc, 57, v183
	s_nop 1
	v_cndmask_b32_e32 v94, v176, v94, vcc
	v_cmp_lt_i32_e32 vcc, 26, v183
	s_nop 1
	v_cndmask_b32_e32 v111, v176, v111, vcc
	v_cmp_lt_i32_e32 vcc, 58, v183
	s_nop 1
	v_cndmask_b32_e32 v95, v176, v95, vcc
; DI float xhalf(float v) { return __shfl_xor(v, 32); }
; DI float fexp2(float x) { return __builtin_amdgcn_exp2f(x); }
; DI void diff_stage(const unsigned char* lds, LAS unsigned char* lds3, int buf, int t, int comp, int q0, int r32, int hi, int vlane, bool skew,
;                    const bf16x8 (&qf)[4], f32x16 (&o)[4], float& m, float& l, bf16x8 (&pp)[4], int& pvo, bool& have_prev) {
;     ...
;     float mx = fmaxf(fmaxf(s0[0], s0[1]), s1[0]);
; #pragma unroll
;     for (int i = 1; i < 15; i += 2) { mx = fmaxf(fmaxf(mx, s0[i + 1]), s0[i + 2 > 15 ? 15 : i + 2]); mx = fmaxf(fmaxf(mx, s1[i]), s1[i + 1]); }
;     mx = fmaxf(mx, s1[15]);
;     mx = fmaxf(mx, xhalf(mx)) * SCL2;
;     if (__any(mx > m + 8.f)) {
;         const float mn = fmaxf(m, mx), al = fexp2(m - mn); l *= al; m = mn;
; #pragma unroll
;         for (int dt = 0; dt < 4; ++dt)
; #pragma unroll
;             for (int i = 0; i < 16; ++i) o[dt][i] *= al;
;     }
.Ldf2a_nodiag:
	v_max3_f32 v1, v96, v97, v98
	v_max3_f32 v1, v1, v99, v100
	v_max3_f32 v1, v1, v101, v102
	v_max3_f32 v1, v1, v103, v104
	v_max3_f32 v1, v1, v105, v106
	v_max3_f32 v1, v1, v107, v108
	v_max3_f32 v1, v1, v109, v110
	v_max3_f32 v1, v1, v111, v80
	v_max3_f32 v1, v1, v81, v82
	v_max3_f32 v1, v1, v83, v84
	v_max3_f32 v1, v1, v85, v86
	v_max3_f32 v1, v1, v87, v88
	v_max3_f32 v1, v1, v89, v90
	v_max3_f32 v1, v1, v91, v92
	v_max3_f32 v1, v1, v93, v94
	v_max_f32_e32 v1, v1, v95
	v_mov_b32_e32 v14, v1
	s_nop 1
	v_permlane32_swap_b32_e32 v1, v14
	v_add_f32_e32 v15, 0x41000000, v185
	v_max_f32_e32 v1, v1, v14
	v_mul_f32_e32 v1, 0x3e38aa3b, v1
	v_cmp_gt_f32_e32 vcc, v1, v15
	s_cbranch_vccz .Ldf2a_notrig
	v_max_f32_e32 v1, v1, v1
	v_max_f32_e32 v14, v185, v185
	v_max_f32_e32 v1, v14, v1
	v_sub_f32_e32 v14, v185, v1
	v_exp_f32_e32 v206, v14
	v_mov_b32_e32 v185, v1
	v_pk_mul_f32 v[78:79], v[78:79], v[206:207] op_sel_hi:[1,0]
	v_pk_mul_f32 v[76:77], v[76:77], v[206:207] op_sel_hi:[1,0]
	v_pk_mul_f32 v[74:75], v[74:75], v[206:207] op_sel_hi:[1,0]
	v_pk_mul_f32 v[72:73], v[72:73], v[206:207] op_sel_hi:[1,0]
	v_pk_mul_f32 v[70:71], v[70:71], v[206:207] op_sel_hi:[1,0]
	v_pk_mul_f32 v[68:69], v[68:69], v[206:207] op_sel_hi:[1,0]
	v_pk_mul_f32 v[66:67], v[66:67], v[206:207] op_sel_hi:[1,0]
	v_pk_mul_f32 v[64:65], v[64:65], v[206:207] op_sel_hi:[1,0]
	v_pk_mul_f32 v[62:63], v[62:63], v[206:207] op_sel_hi:[1,0]
	v_pk_mul_f32 v[60:61], v[60:61], v[206:207] op_sel_hi:[1,0]
	v_pk_mul_f32 v[58:59], v[58:59], v[206:207] op_sel_hi:[1,0]
	v_pk_mul_f32 v[56:57], v[56:57], v[206:207] op_sel_hi:[1,0]
	v_pk_mul_f32 v[54:55], v[54:55], v[206:207] op_sel_hi:[1,0]
	v_pk_mul_f32 v[52:53], v[52:53], v[206:207] op_sel_hi:[1,0]
	v_pk_mul_f32 v[50:51], v[50:51], v[206:207] op_sel_hi:[1,0]
	v_pk_mul_f32 v[48:49], v[48:49], v[206:207] op_sel_hi:[1,0]
	v_pk_mul_f32 v[46:47], v[46:47], v[206:207] op_sel_hi:[1,0]
	v_pk_mul_f32 v[44:45], v[44:45], v[206:207] op_sel_hi:[1,0]
	v_pk_mul_f32 v[42:43], v[42:43], v[206:207] op_sel_hi:[1,0]
	v_pk_mul_f32 v[40:41], v[40:41], v[206:207] op_sel_hi:[1,0]
	v_pk_mul_f32 v[38:39], v[38:39], v[206:207] op_sel_hi:[1,0]
	v_pk_mul_f32 v[36:37], v[36:37], v[206:207] op_sel_hi:[1,0]
	v_pk_mul_f32 v[34:35], v[34:35], v[206:207] op_sel_hi:[1,0]
	v_pk_mul_f32 v[32:33], v[32:33], v[206:207] op_sel_hi:[1,0]
	v_pk_mul_f32 v[30:31], v[30:31], v[206:207] op_sel_hi:[1,0]
	v_pk_mul_f32 v[28:29], v[28:29], v[206:207] op_sel_hi:[1,0]
	v_pk_mul_f32 v[26:27], v[26:27], v[206:207] op_sel_hi:[1,0]
	v_pk_mul_f32 v[24:25], v[24:25], v[206:207] op_sel_hi:[1,0]
	v_pk_mul_f32 v[22:23], v[22:23], v[206:207] op_sel_hi:[1,0]
	v_pk_mul_f32 v[20:21], v[20:21], v[206:207] op_sel_hi:[1,0]
	v_pk_mul_f32 v[18:19], v[18:19], v[206:207] op_sel_hi:[1,0]
	v_pk_mul_f32 v[16:17], v[16:17], v[206:207] op_sel_hi:[1,0]
	v_mul_f32_e32 v143, v143, v206
; DI float fexp2(float x) { return __builtin_amdgcn_exp2f(x); }
; #define DF_VLD(VF, VOFF, H) do { _Pragma("unroll") for (int d2 = 0; d2 < 2; ++d2) { LAS unsigned char* vb_ = lds3 + (VOFF) + (2 * (H) + d2) * 4096; VF[2 * d2] = vfrag(vb_); VF[2 * d2 + 1] = vfrag(vb_ + 1024); } } while (0)
; #define DF_PVM(VF, P0, P1, H) do { _Pragma("unroll") for (int d2 = 0; d2 < 2; ++d2) { o[2 * (H) + d2] = mfma32(VF[2 * d2], P0, o[2 * (H) + d2]); o[2 * (H) + d2] = mfma32(VF[2 * d2 + 1], P1, o[2 * (H) + d2]); } } while (0)
; DI void diff_stage(const unsigned char* lds, LAS unsigned char* lds3, int buf, int t, int comp, int q0, int r32, int hi, int vlane, bool skew,
;                    const bf16x8 (&qf)[4], f32x16 (&o)[4], float& m, float& l, bf16x8 (&pp)[4], int& pvo, bool& have_prev) {
;     ...
;     float sum0 = 0.f, sum1 = 0.f;
; #pragma unroll
;     for (int i = 0; i < 16; ++i) { s0[i] = fexp2(__builtin_fmaf(s0[i], SCL2, -m)); sum0 += s0[i]; s1[i] = fexp2(__builtin_fmaf(s1[i], SCL2, -m)); sum1 += s1[i]; }
;     l += sum0 + sum1;
;     const int vo = buf * DF_STAGE + DF_V + vlane;
;     if (!skew) {
;         const bf16x8 p00 = packP<0>(s0), p01 = packP<1>(s0);
;         DF_VLD(vf, vo, 0); DF_PVM(vf, p00, p01, 0); DF_VLD(vf, vo, 1); DF_PVM(vf, p00, p01, 1);
;         const bf16x8 p10 = packP<0>(s1), p11 = packP<1>(s1);
;         DF_VLD(vf, vo + 2048, 0); DF_PVM(vf, p10, p11, 0); DF_VLD(vf, vo + 2048, 1); DF_PVM(vf, p10, p11, 1);
.Ldf2a_notrig:
	v_fma_f32 v96, v96, s44, -v185
	v_fma_f32 v97, v97, s44, -v185
	v_exp_f32_e32 v96, v96
	v_exp_f32_e32 v97, v97
	v_fma_f32 v98, v98, s44, -v185
	v_fma_f32 v99, v99, s44, -v185
	v_exp_f32_e32 v98, v98
	v_exp_f32_e32 v99, v99
	v_fma_f32 v100, v100, s44, -v185
	v_fma_f32 v101, v101, s44, -v185
	v_exp_f32_e32 v100, v100
	v_exp_f32_e32 v101, v101
	v_fma_f32 v102, v102, s44, -v185
	v_fma_f32 v103, v103, s44, -v185
	v_exp_f32_e32 v102, v102
	v_exp_f32_e32 v103, v103
	v_fma_f32 v104, v104, s44, -v185
	v_fma_f32 v105, v105, s44, -v185
	v_exp_f32_e32 v104, v104
	v_exp_f32_e32 v105, v105
	v_fma_f32 v106, v106, s44, -v185
	v_fma_f32 v107, v107, s44, -v185
	v_exp_f32_e32 v106, v106
	v_exp_f32_e32 v107, v107
	v_fma_f32 v108, v108, s44, -v185
	v_fma_f32 v109, v109, s44, -v185
	v_exp_f32_e32 v108, v108
	v_exp_f32_e32 v109, v109
	v_fma_f32 v110, v110, s44, -v185
	v_fma_f32 v111, v111, s44, -v185
	v_exp_f32_e32 v110, v110
	v_exp_f32_e32 v111, v111
	v_add_f32_e32 v14, v96, v97
	v_add_f32_e32 v14, v14, v98
	v_add_f32_e32 v14, v14, v99
	v_add_f32_e32 v14, v14, v100
	v_add_f32_e32 v14, v14, v101
	v_add_f32_e32 v14, v14, v102
	v_add_f32_e32 v14, v14, v103
	v_add_f32_e32 v14, v14, v104
	v_add_f32_e32 v14, v14, v105
	v_add_f32_e32 v14, v14, v106
	v_add_f32_e32 v14, v14, v107
	v_add_f32_e32 v14, v14, v108
	v_add_f32_e32 v14, v14, v109
	v_add_f32_e32 v14, v14, v110
	v_add_f32_e32 v14, v14, v111
	v_fma_f32 v80, v80, s44, -v185
	v_fma_f32 v81, v81, s44, -v185
	v_exp_f32_e32 v80, v80
	v_exp_f32_e32 v81, v81
	v_fma_f32 v82, v82, s44, -v185
	v_fma_f32 v83, v83, s44, -v185
	v_exp_f32_e32 v82, v82
	v_exp_f32_e32 v83, v83
	v_fma_f32 v84, v84, s44, -v185
	v_fma_f32 v85, v85, s44, -v185
	v_exp_f32_e32 v84, v84
	v_exp_f32_e32 v85, v85
	v_fma_f32 v86, v86, s44, -v185
	v_fma_f32 v87, v87, s44, -v185
	v_exp_f32_e32 v86, v86
	v_exp_f32_e32 v87, v87
	v_fma_f32 v88, v88, s44, -v185
	v_fma_f32 v89, v89, s44, -v185
	v_exp_f32_e32 v88, v88
	v_exp_f32_e32 v89, v89
	v_fma_f32 v90, v90, s44, -v185
	v_fma_f32 v91, v91, s44, -v185
	v_exp_f32_e32 v90, v90
	v_exp_f32_e32 v91, v91
	v_fma_f32 v92, v92, s44, -v185
	v_fma_f32 v93, v93, s44, -v185
	v_exp_f32_e32 v92, v92
	v_exp_f32_e32 v93, v93
	v_fma_f32 v94, v94, s44, -v185
	v_fma_f32 v95, v95, s44, -v185
	v_exp_f32_e32 v94, v94
	v_exp_f32_e32 v95, v95
	v_add_f32_e32 v15, v80, v81
	v_add_f32_e32 v15, v15, v82
	v_add_f32_e32 v15, v15, v83
	v_add_f32_e32 v15, v15, v84
	v_add_f32_e32 v15, v15, v85
	v_add_f32_e32 v15, v15, v86
	v_add_f32_e32 v15, v15, v87
	v_add_f32_e32 v15, v15, v88
	v_add_f32_e32 v15, v15, v89
	v_add_f32_e32 v15, v15, v90
	v_add_f32_e32 v15, v15, v91
	v_add_f32_e32 v15, v15, v92
	v_add_f32_e32 v15, v15, v93
	v_add_f32_e32 v15, v15, v94
	v_add_f32_e32 v15, v15, v95
	v_add_f32_e32 v14, v14, v15
	v_add_f32_e32 v143, v143, v14
	v_cvt_pk_bf16_f32 v240, v96, v97
	v_cvt_pk_bf16_f32 v241, v98, v99
	v_cvt_pk_bf16_f32 v242, v100, v101
	v_cvt_pk_bf16_f32 v243, v102, v103
	v_cvt_pk_bf16_f32 v244, v104, v105
	v_cvt_pk_bf16_f32 v245, v106, v107
	v_cvt_pk_bf16_f32 v246, v108, v109
	v_cvt_pk_bf16_f32 v247, v110, v111
	v_cvt_pk_bf16_f32 v248, v80, v81
	v_cvt_pk_bf16_f32 v249, v82, v83
	v_cvt_pk_bf16_f32 v250, v84, v85
	v_cvt_pk_bf16_f32 v251, v86, v87
	v_cvt_pk_bf16_f32 v252, v88, v89
	v_cvt_pk_bf16_f32 v253, v90, v91
	v_cvt_pk_bf16_f32 v254, v92, v93
	v_cvt_pk_bf16_f32 v255, v94, v95
	s_nop 1
	s_waitcnt lgkmcnt(10)
	v_mfma_f32_32x32x16_bf16 v[64:79], v[208:211], v[240:243], v[64:79]
	ds_read_b64_tr_b16 v[232:233], v6 offset:28672
	ds_read_b64_tr_b16 v[234:235], v6 offset:29184
	s_waitcnt lgkmcnt(10)
	v_mfma_f32_32x32x16_bf16 v[64:79], v[212:215], v[244:247], v[64:79]
	ds_read_b64_tr_b16 v[236:237], v6 offset:29696
	ds_read_b64_tr_b16 v[238:239], v6 offset:30208
	s_waitcnt lgkmcnt(10)
	v_mfma_f32_32x32x16_bf16 v[48:63], v[216:219], v[240:243], v[48:63]
	ds_read_b64_tr_b16 v[208:209], v6 offset:18432
	ds_read_b64_tr_b16 v[210:211], v6 offset:18944
	s_waitcnt lgkmcnt(10)
	v_mfma_f32_32x32x16_bf16 v[48:63], v[220:223], v[244:247], v[48:63]
	ds_read_b64_tr_b16 v[212:213], v6 offset:19456
	ds_read_b64_tr_b16 v[214:215], v6 offset:19968
	s_waitcnt lgkmcnt(10)
	v_mfma_f32_32x32x16_bf16 v[32:47], v[224:227], v[240:243], v[32:47]
	ds_read_b64_tr_b16 v[216:217], v6 offset:22528
	ds_read_b64_tr_b16 v[218:219], v6 offset:23040
	s_waitcnt lgkmcnt(10)
	v_mfma_f32_32x32x16_bf16 v[32:47], v[228:231], v[244:247], v[32:47]
	ds_read_b64_tr_b16 v[220:221], v6 offset:23552
	ds_read_b64_tr_b16 v[222:223], v6 offset:24064
	s_waitcnt lgkmcnt(10)
	v_mfma_f32_32x32x16_bf16 v[16:31], v[232:235], v[240:243], v[16:31]
	ds_read_b64_tr_b16 v[224:225], v6 offset:26624
	ds_read_b64_tr_b16 v[226:227], v6 offset:27136
	s_waitcnt lgkmcnt(10)
	v_mfma_f32_32x32x16_bf16 v[16:31], v[236:239], v[244:247], v[16:31]
	ds_read_b64_tr_b16 v[228:229], v6 offset:27648
	ds_read_b64_tr_b16 v[230:231], v6 offset:28160
	s_waitcnt lgkmcnt(10)
	v_mfma_f32_32x32x16_bf16 v[64:79], v[208:211], v[248:251], v[64:79]
	ds_read_b64_tr_b16 v[232:233], v6 offset:30720
	ds_read_b64_tr_b16 v[234:235], v6 offset:31232
	s_waitcnt lgkmcnt(10)
	v_mfma_f32_32x32x16_bf16 v[64:79], v[212:215], v[252:255], v[64:79]
	ds_read_b64_tr_b16 v[236:237], v6 offset:31744
	ds_read_b64_tr_b16 v[238:239], v6 offset:32256
	s_waitcnt lgkmcnt(10)
	v_mfma_f32_32x32x16_bf16 v[48:63], v[216:219], v[248:251], v[48:63]
	s_waitcnt lgkmcnt(8)
	v_mfma_f32_32x32x16_bf16 v[48:63], v[220:223], v[252:255], v[48:63]
	s_waitcnt lgkmcnt(6)
	v_mfma_f32_32x32x16_bf16 v[32:47], v[224:227], v[248:251], v[32:47]
	s_waitcnt lgkmcnt(4)
	v_mfma_f32_32x32x16_bf16 v[32:47], v[228:231], v[252:255], v[32:47]
	s_waitcnt lgkmcnt(2)
	v_mfma_f32_32x32x16_bf16 v[16:31], v[232:235], v[248:251], v[16:31]
	s_waitcnt lgkmcnt(0)
	v_mfma_f32_32x32x16_bf16 v[16:31], v[236:239], v[252:255], v[16:31]
	s_branch .Ldf2a_bar
